# GEMM mainloops: removed the compiler-duplicated s_waitcnt lgkmcnt(0) at the head of 6 of 8 MFMA segments (30 sites) on top of s_setprio deletion
# speedup vs baseline: 1.0165x; 1.0022x over previous
.LBB0_422:
	s_add_u32 s54, s52, 0xfffc0080
	s_addc_u32 s55, s53, -1
	s_add_i32 s68, 0, 0x10000
	v_add_u32_e32 v142, s68, v187
	ds_read_b128 v[130:133], v142
	ds_read_b128 v[134:137], v142 offset:1024
	ds_read_b128 v[138:141], v142 offset:2048
	ds_read_b128 v[142:145], v142 offset:3072
	s_cmp_eq_u32 s23, 12
	s_cselect_b32 s57, s5, s55
	s_cselect_b32 s56, s90, s54
	s_cselect_b32 s55, s1, s22
	s_cselect_b32 s54, s91, s94
	v_lshl_add_u64 v[184:185], s[52:53], 0, v[172:173]
	s_add_i32 m0, s41, 0xc000
	ds_read_b128 v[146:149], v189
	ds_read_b128 v[150:153], v189 offset:1024
	ds_read_b128 v[154:157], v189 offset:2048
	ds_read_b128 v[158:161], v189 offset:3072
	ds_read_b128 v[162:165], v189 offset:4096
	ds_read_b128 v[166:169], v189 offset:5120
	ds_read_b128 v[180:183], v189 offset:6144
	ds_read_b128 v[210:213], v189 offset:7168
	global_load_lds_dwordx4 v[184:185], off
	v_lshl_add_u64 v[184:185], s[52:53], 0, v[178:179]
	s_add_i32 m0, s41, 0xe000
	s_nop 0
	global_load_lds_dwordx4 v[184:185], off
	s_waitcnt lgkmcnt(8)
	s_barrier
	s_waitcnt lgkmcnt(0)


	v_mfma_f32_16x16x32_bf16 v[118:121], v[130:133], v[146:149], v[118:121]
	v_mfma_f32_16x16x32_bf16 v[126:129], v[138:141], v[146:149], v[126:129]
	v_mfma_f32_16x16x32_bf16 v[114:117], v[130:133], v[154:157], v[114:117]
	v_mfma_f32_16x16x32_bf16 v[122:125], v[138:141], v[154:157], v[122:125]
	v_mfma_f32_16x16x32_bf16 v[106:109], v[130:133], v[162:165], v[106:109]
	v_mfma_f32_16x16x32_bf16 v[110:113], v[138:141], v[162:165], v[110:113]
	v_mfma_f32_16x16x32_bf16 v[98:101], v[130:133], v[180:183], v[98:101]
	v_mfma_f32_16x16x32_bf16 v[102:105], v[138:141], v[180:183], v[102:105]
	v_mfma_f32_16x16x32_bf16 v[118:121], v[134:137], v[150:153], v[118:121]
	v_mfma_f32_16x16x32_bf16 v[126:129], v[142:145], v[150:153], v[126:129]
	v_mfma_f32_16x16x32_bf16 v[114:117], v[134:137], v[158:161], v[114:117]
	v_mfma_f32_16x16x32_bf16 v[122:125], v[142:145], v[158:161], v[122:125]
	v_mfma_f32_16x16x32_bf16 v[106:109], v[134:137], v[166:169], v[106:109]
	v_mfma_f32_16x16x32_bf16 v[110:113], v[142:145], v[166:169], v[110:113]
	v_mfma_f32_16x16x32_bf16 v[98:101], v[134:137], v[210:213], v[98:101]
	v_mfma_f32_16x16x32_bf16 v[102:105], v[142:145], v[210:213], v[102:105]

	s_barrier
	s_add_i32 s70, 0, 0x14000
	v_add_u32_e32 v184, s70, v187
	s_add_i32 s68, s68, s40
	ds_read_b128 v[214:217], v184
	ds_read_b128 v[218:221], v184 offset:1024
	ds_read_b128 v[222:225], v184 offset:2048
	ds_read_b128 v[226:229], v184 offset:3072
	v_lshl_add_u64 v[184:185], s[54:55], 0, v[0:1]
	s_mov_b32 m0, s68
	v_lshl_add_u64 v[190:191], s[54:55], 0, v[170:171]
	global_load_lds_dwordx4 v[184:185], off
	s_add_i32 m0, s68, 0x2000
	s_nop 0
	global_load_lds_dwordx4 v[190:191], off
	s_barrier
	s_waitcnt lgkmcnt(0)


	v_mfma_f32_16x16x32_bf16 v[66:69], v[214:217], v[146:149], v[66:69]
	v_mfma_f32_16x16x32_bf16 v[70:73], v[222:225], v[146:149], v[70:73]
	v_mfma_f32_16x16x32_bf16 v[50:53], v[214:217], v[154:157], v[50:53]
	v_mfma_f32_16x16x32_bf16 v[54:57], v[222:225], v[154:157], v[54:57]
	v_mfma_f32_16x16x32_bf16 v[42:45], v[214:217], v[162:165], v[42:45]
	v_mfma_f32_16x16x32_bf16 v[46:49], v[222:225], v[162:165], v[46:49]
	v_mfma_f32_16x16x32_bf16 v[34:37], v[214:217], v[180:183], v[34:37]
	v_mfma_f32_16x16x32_bf16 v[38:41], v[222:225], v[180:183], v[38:41]
	v_mfma_f32_16x16x32_bf16 v[66:69], v[218:221], v[150:153], v[66:69]
	v_mfma_f32_16x16x32_bf16 v[70:73], v[226:229], v[150:153], v[70:73]
	v_mfma_f32_16x16x32_bf16 v[50:53], v[218:221], v[158:161], v[50:53]
	v_mfma_f32_16x16x32_bf16 v[54:57], v[226:229], v[158:161], v[54:57]
	v_mfma_f32_16x16x32_bf16 v[42:45], v[218:221], v[166:169], v[42:45]
	v_mfma_f32_16x16x32_bf16 v[46:49], v[226:229], v[166:169], v[46:49]
	v_mfma_f32_16x16x32_bf16 v[34:37], v[218:221], v[210:213], v[34:37]
	v_mfma_f32_16x16x32_bf16 v[38:41], v[226:229], v[210:213], v[38:41]

	s_mov_b32 m0, s41
	v_lshl_add_u64 v[202:203], s[56:57], 0, v[0:1]
	s_barrier
	ds_read_b128 v[146:149], v189 offset:16384
	ds_read_b128 v[150:153], v189 offset:17408
	ds_read_b128 v[154:157], v189 offset:18432
	ds_read_b128 v[158:161], v189 offset:19456
	ds_read_b128 v[162:165], v189 offset:20480
	ds_read_b128 v[166:169], v189 offset:21504
	ds_read_b128 v[180:183], v189 offset:22528
	ds_read_b128 v[210:213], v189 offset:23552
	global_load_lds_dwordx4 v[202:203], off
	v_lshl_add_u64 v[204:205], s[56:57], 0, v[170:171]
	s_mov_b32 m0, s42
	s_nop 0
	global_load_lds_dwordx4 v[204:205], off
	s_barrier
	s_waitcnt lgkmcnt(0)


	v_mfma_f32_16x16x32_bf16 v[90:93], v[130:133], v[146:149], v[90:93]
	v_mfma_f32_16x16x32_bf16 v[94:97], v[138:141], v[146:149], v[94:97]
	v_mfma_f32_16x16x32_bf16 v[82:85], v[130:133], v[154:157], v[82:85]
	v_mfma_f32_16x16x32_bf16 v[86:89], v[138:141], v[154:157], v[86:89]
	v_mfma_f32_16x16x32_bf16 v[74:77], v[130:133], v[162:165], v[74:77]
	v_mfma_f32_16x16x32_bf16 v[78:81], v[138:141], v[162:165], v[78:81]
	v_mfma_f32_16x16x32_bf16 v[58:61], v[130:133], v[180:183], v[58:61]
	v_mfma_f32_16x16x32_bf16 v[62:65], v[138:141], v[180:183], v[62:65]
	v_mfma_f32_16x16x32_bf16 v[90:93], v[134:137], v[150:153], v[90:93]
	v_mfma_f32_16x16x32_bf16 v[94:97], v[142:145], v[150:153], v[94:97]
	v_mfma_f32_16x16x32_bf16 v[82:85], v[134:137], v[158:161], v[82:85]
	v_mfma_f32_16x16x32_bf16 v[86:89], v[142:145], v[158:161], v[86:89]
	v_mfma_f32_16x16x32_bf16 v[74:77], v[134:137], v[166:169], v[74:77]
	v_mfma_f32_16x16x32_bf16 v[78:81], v[142:145], v[166:169], v[78:81]
	v_mfma_f32_16x16x32_bf16 v[58:61], v[134:137], v[210:213], v[58:61]
	v_mfma_f32_16x16x32_bf16 v[62:65], v[142:145], v[210:213], v[62:65]

	s_barrier
	s_add_u32 s68, s54, 0x40000
	s_addc_u32 s69, s55, 0
	s_add_i32 s70, s70, s40
	v_lshl_add_u64 v[130:131], s[68:69], 0, v[0:1]
	s_mov_b32 m0, s70
	s_nop 0
	global_load_lds_dwordx4 v[130:131], off
	v_lshl_add_u64 v[130:131], s[68:69], 0, v[170:171]
	s_add_i32 m0, s70, 0x2000
	s_nop 0
	global_load_lds_dwordx4 v[130:131], off
	s_waitcnt vmcnt(6)
	s_barrier

	v_mfma_f32_16x16x32_bf16 v[26:29], v[214:217], v[146:149], v[26:29]
	v_mfma_f32_16x16x32_bf16 v[30:33], v[222:225], v[146:149], v[30:33]
	v_mfma_f32_16x16x32_bf16 v[18:21], v[214:217], v[154:157], v[18:21]
	v_mfma_f32_16x16x32_bf16 v[22:25], v[222:225], v[154:157], v[22:25]
	v_mfma_f32_16x16x32_bf16 v[10:13], v[214:217], v[162:165], v[10:13]
	v_mfma_f32_16x16x32_bf16 v[14:17], v[222:225], v[162:165], v[14:17]
	v_mfma_f32_16x16x32_bf16 v[2:5], v[214:217], v[180:183], v[2:5]
	v_mfma_f32_16x16x32_bf16 v[6:9], v[222:225], v[180:183], v[6:9]
	v_mfma_f32_16x16x32_bf16 v[26:29], v[218:221], v[150:153], v[26:29]
	v_mfma_f32_16x16x32_bf16 v[30:33], v[226:229], v[150:153], v[30:33]
	v_mfma_f32_16x16x32_bf16 v[18:21], v[218:221], v[158:161], v[18:21]
	v_mfma_f32_16x16x32_bf16 v[22:25], v[226:229], v[158:161], v[22:25]
	v_mfma_f32_16x16x32_bf16 v[10:13], v[218:221], v[166:169], v[10:13]
	v_mfma_f32_16x16x32_bf16 v[14:17], v[226:229], v[166:169], v[14:17]
	v_mfma_f32_16x16x32_bf16 v[2:5], v[218:221], v[210:213], v[2:5]
	v_mfma_f32_16x16x32_bf16 v[6:9], v[226:229], v[210:213], v[6:9]

	s_add_i32 s68, 0, 0x18000
	v_add_u32_e32 v142, s68, v187
	s_barrier
	ds_read_b128 v[130:133], v142
	ds_read_b128 v[134:137], v142 offset:1024
	ds_read_b128 v[138:141], v142 offset:2048
	ds_read_b128 v[142:145], v142 offset:3072
	s_add_u32 s56, s56, 0x40000
	s_addc_u32 s57, s57, 0
	s_mov_b32 m0, s43
	v_lshl_add_u64 v[214:215], s[56:57], 0, v[0:1]
	ds_read_b128 v[146:149], v189 offset:32768
	ds_read_b128 v[150:153], v189 offset:33792
	ds_read_b128 v[154:157], v189 offset:34816
	ds_read_b128 v[158:161], v189 offset:35840
	ds_read_b128 v[162:165], v189 offset:36864
	ds_read_b128 v[166:169], v189 offset:37888
	ds_read_b128 v[180:183], v189 offset:38912
	ds_read_b128 v[210:213], v189 offset:39936
	global_load_lds_dwordx4 v[214:215], off
	v_lshl_add_u64 v[214:215], s[56:57], 0, v[170:171]
	s_mov_b32 m0, s58
	s_nop 0
	global_load_lds_dwordx4 v[214:215], off
	s_waitcnt lgkmcnt(8)
	s_barrier
	s_waitcnt lgkmcnt(0)


	v_mfma_f32_16x16x32_bf16 v[118:121], v[130:133], v[146:149], v[118:121]
	v_mfma_f32_16x16x32_bf16 v[126:129], v[138:141], v[146:149], v[126:129]
	v_mfma_f32_16x16x32_bf16 v[114:117], v[130:133], v[154:157], v[114:117]
	v_mfma_f32_16x16x32_bf16 v[122:125], v[138:141], v[154:157], v[122:125]
	v_mfma_f32_16x16x32_bf16 v[106:109], v[130:133], v[162:165], v[106:109]
	v_mfma_f32_16x16x32_bf16 v[110:113], v[138:141], v[162:165], v[110:113]
	v_mfma_f32_16x16x32_bf16 v[98:101], v[130:133], v[180:183], v[98:101]
	v_mfma_f32_16x16x32_bf16 v[102:105], v[138:141], v[180:183], v[102:105]
	v_mfma_f32_16x16x32_bf16 v[118:121], v[134:137], v[150:153], v[118:121]
	v_mfma_f32_16x16x32_bf16 v[126:129], v[142:145], v[150:153], v[126:129]
	v_mfma_f32_16x16x32_bf16 v[114:117], v[134:137], v[158:161], v[114:117]
	v_mfma_f32_16x16x32_bf16 v[122:125], v[142:145], v[158:161], v[122:125]
	v_mfma_f32_16x16x32_bf16 v[106:109], v[134:137], v[166:169], v[106:109]
	v_mfma_f32_16x16x32_bf16 v[110:113], v[142:145], v[166:169], v[110:113]
	v_mfma_f32_16x16x32_bf16 v[98:101], v[134:137], v[210:213], v[98:101]
	v_mfma_f32_16x16x32_bf16 v[102:105], v[142:145], v[210:213], v[102:105]

	s_barrier
	s_add_i32 s56, 0, 0x1c000
	s_add_i32 s57, s68, s40
	v_add_u32_e32 v209, s56, v187
	v_lshl_add_u64 v[184:185], v[184:185], 0, s[60:61]
	s_mov_b32 m0, s57
	ds_read_b128 v[214:217], v209
	ds_read_b128 v[218:221], v209 offset:1024
	ds_read_b128 v[222:225], v209 offset:2048
	ds_read_b128 v[226:229], v209 offset:3072
	global_load_lds_dwordx4 v[184:185], off
	v_lshl_add_u64 v[184:185], v[190:191], 0, s[60:61]
	s_add_i32 m0, s57, 0x2000
	s_nop 0
	global_load_lds_dwordx4 v[184:185], off
	s_barrier
	s_waitcnt lgkmcnt(0)


	v_mfma_f32_16x16x32_bf16 v[66:69], v[214:217], v[146:149], v[66:69]
	v_mfma_f32_16x16x32_bf16 v[70:73], v[222:225], v[146:149], v[70:73]
	v_mfma_f32_16x16x32_bf16 v[50:53], v[214:217], v[154:157], v[50:53]
	v_mfma_f32_16x16x32_bf16 v[54:57], v[222:225], v[154:157], v[54:57]
	v_mfma_f32_16x16x32_bf16 v[42:45], v[214:217], v[162:165], v[42:45]
	v_mfma_f32_16x16x32_bf16 v[46:49], v[222:225], v[162:165], v[46:49]
	v_mfma_f32_16x16x32_bf16 v[34:37], v[214:217], v[180:183], v[34:37]
	v_mfma_f32_16x16x32_bf16 v[38:41], v[222:225], v[180:183], v[38:41]
	v_mfma_f32_16x16x32_bf16 v[66:69], v[218:221], v[150:153], v[66:69]
	v_mfma_f32_16x16x32_bf16 v[70:73], v[226:229], v[150:153], v[70:73]
	v_mfma_f32_16x16x32_bf16 v[50:53], v[218:221], v[158:161], v[50:53]
	v_mfma_f32_16x16x32_bf16 v[54:57], v[226:229], v[158:161], v[54:57]
	v_mfma_f32_16x16x32_bf16 v[42:45], v[218:221], v[166:169], v[42:45]
	v_mfma_f32_16x16x32_bf16 v[46:49], v[226:229], v[166:169], v[46:49]
	v_mfma_f32_16x16x32_bf16 v[34:37], v[218:221], v[210:213], v[34:37]
	v_mfma_f32_16x16x32_bf16 v[38:41], v[226:229], v[210:213], v[38:41]

	s_mov_b32 m0, s63
	v_lshl_add_u64 v[184:185], v[202:203], 0, s[60:61]
	s_barrier
	ds_read_b128 v[146:149], v189 offset:49152
	ds_read_b128 v[150:153], v189 offset:50176
	ds_read_b128 v[154:157], v189 offset:51200
	ds_read_b128 v[158:161], v189 offset:52224
	ds_read_b128 v[162:165], v189 offset:53248
	ds_read_b128 v[166:169], v189 offset:54272
	ds_read_b128 v[180:183], v189 offset:55296
	ds_read_b128 v[210:213], v189 offset:56320
	global_load_lds_dwordx4 v[184:185], off
	v_lshl_add_u64 v[184:185], v[204:205], 0, s[60:61]
	s_mov_b32 m0, s64
	s_nop 0
	global_load_lds_dwordx4 v[184:185], off
	s_barrier
	s_waitcnt lgkmcnt(0)


	v_mfma_f32_16x16x32_bf16 v[90:93], v[130:133], v[146:149], v[90:93]
	v_mfma_f32_16x16x32_bf16 v[94:97], v[138:141], v[146:149], v[94:97]
	v_mfma_f32_16x16x32_bf16 v[82:85], v[130:133], v[154:157], v[82:85]
	v_mfma_f32_16x16x32_bf16 v[86:89], v[138:141], v[154:157], v[86:89]
	v_mfma_f32_16x16x32_bf16 v[74:77], v[130:133], v[162:165], v[74:77]
	v_mfma_f32_16x16x32_bf16 v[78:81], v[138:141], v[162:165], v[78:81]
	v_mfma_f32_16x16x32_bf16 v[58:61], v[130:133], v[180:183], v[58:61]
	v_mfma_f32_16x16x32_bf16 v[62:65], v[138:141], v[180:183], v[62:65]
	v_mfma_f32_16x16x32_bf16 v[90:93], v[134:137], v[150:153], v[90:93]
	v_mfma_f32_16x16x32_bf16 v[94:97], v[142:145], v[150:153], v[94:97]
	v_mfma_f32_16x16x32_bf16 v[82:85], v[134:137], v[158:161], v[82:85]
	v_mfma_f32_16x16x32_bf16 v[86:89], v[142:145], v[158:161], v[86:89]
	v_mfma_f32_16x16x32_bf16 v[74:77], v[134:137], v[166:169], v[74:77]
	v_mfma_f32_16x16x32_bf16 v[78:81], v[142:145], v[166:169], v[78:81]
	v_mfma_f32_16x16x32_bf16 v[58:61], v[134:137], v[210:213], v[58:61]
	v_mfma_f32_16x16x32_bf16 v[62:65], v[142:145], v[210:213], v[62:65]

	s_barrier
	s_add_u32 s54, s54, 0x40080
	s_addc_u32 s55, s55, 0
	s_add_i32 s56, s56, s40
	v_lshl_add_u64 v[130:131], s[54:55], 0, v[0:1]
	s_mov_b32 m0, s56
	s_nop 0
	global_load_lds_dwordx4 v[130:131], off
	v_lshl_add_u64 v[130:131], s[54:55], 0, v[170:171]
	s_add_i32 m0, s56, 0x2000
	s_nop 0
	global_load_lds_dwordx4 v[130:131], off
	s_waitcnt vmcnt(6)
	s_barrier

	v_mfma_f32_16x16x32_bf16 v[26:29], v[214:217], v[146:149], v[26:29]
	v_mfma_f32_16x16x32_bf16 v[30:33], v[222:225], v[146:149], v[30:33]
	v_mfma_f32_16x16x32_bf16 v[18:21], v[214:217], v[154:157], v[18:21]
	v_mfma_f32_16x16x32_bf16 v[22:25], v[222:225], v[154:157], v[22:25]
	v_mfma_f32_16x16x32_bf16 v[10:13], v[214:217], v[162:165], v[10:13]
	v_mfma_f32_16x16x32_bf16 v[14:17], v[222:225], v[162:165], v[14:17]
	v_mfma_f32_16x16x32_bf16 v[2:5], v[214:217], v[180:183], v[2:5]
	v_mfma_f32_16x16x32_bf16 v[6:9], v[222:225], v[180:183], v[6:9]
	v_mfma_f32_16x16x32_bf16 v[26:29], v[218:221], v[150:153], v[26:29]
	v_mfma_f32_16x16x32_bf16 v[30:33], v[226:229], v[150:153], v[30:33]
	v_mfma_f32_16x16x32_bf16 v[18:21], v[218:221], v[158:161], v[18:21]
	v_mfma_f32_16x16x32_bf16 v[22:25], v[226:229], v[158:161], v[22:25]
	v_mfma_f32_16x16x32_bf16 v[10:13], v[218:221], v[166:169], v[10:13]
	v_mfma_f32_16x16x32_bf16 v[14:17], v[226:229], v[166:169], v[14:17]
	v_mfma_f32_16x16x32_bf16 v[2:5], v[218:221], v[210:213], v[2:5]
	v_mfma_f32_16x16x32_bf16 v[6:9], v[226:229], v[210:213], v[6:9]

	s_add_i32 s23, s23, 2
	s_add_u32 s52, s52, 0x100
	s_addc_u32 s53, s53, 0
	s_add_u32 s94, s94, 0x100
	s_addc_u32 s22, s22, 0
	s_cmp_gt_u32 s23, 13
	s_barrier
	s_cbranch_scc0 .LBB0_422
	s_sub_i32 s1, s67, 32
	s_lshr_b32 s1, s1, 2
	s_add_i32 s1, s1, 1
	s_cmp_gt_i32 s67, 31
	s_cselect_b32 s1, s1, 0
	v_lshl_or_b32 v134, s66, 7, v188
	v_lshl_add_u32 v130, s67, 8, v186
	s_mul_hi_u32 s5, s1, 0x6000
	s_mulk_i32 s1, 0x6000
	v_ashrrev_i32_e32 v135, 31, v134
	s_add_u32 s22, s59, s1
	v_ashrrev_i32_e32 v131, 31, v130
	v_lshlrev_b64 v[180:181], 2, v[134:135]
	s_addc_u32 s23, s62, s5
	v_lshlrev_b64 v[132:133], 12, v[130:131]
	v_lshl_add_u64 v[134:135], s[26:27], 0, v[180:181]
	v_lshl_add_u64 v[190:191], s[22:23], 0, v[180:181]
	v_lshl_add_u64 v[136:137], v[134:135], 0, v[132:133]
	global_load_dwordx4 v[150:153], v[190:191], off
	global_load_dwordx4 v[210:213], v[136:137], off
	s_mov_b64 s[22:23], 0x80000
	v_or_b32_e32 v138, 16, v130
	v_mul_f32_e32 v131, 0xbfb8aa3b, v122
	v_mul_f32_e32 v141, 0xbfb8aa3b, v124
	v_mul_f32_e32 v125, 0xbfb8aa3b, v125
	v_or_b32_e32 v122, 32, v130
	v_or_b32_e32 v124, 48, v130
	v_lshl_add_u64 v[234:235], v[132:133], 0, s[22:23]
	s_mov_b64 s[22:23], 0x90000
	v_ashrrev_i32_e32 v139, 31, v138
	v_mul_f32_e32 v140, 0xbfb8aa3b, v123
	v_ashrrev_i32_e32 v123, 31, v122
	v_exp_f32_e32 v248, v125
	v_ashrrev_i32_e32 v125, 31, v124
	v_lshl_add_u64 v[238:239], v[132:133], 0, s[22:23]
	s_mov_b64 s[22:23], 0xa0000
	v_lshlrev_b64 v[202:203], 12, v[138:139]
	v_mul_f32_e32 v126, 0xbfb8aa3b, v126
	v_mul_f32_e32 v127, 0xbfb8aa3b, v127
	v_mul_f32_e32 v128, 0xbfb8aa3b, v128
	v_mul_f32_e32 v129, 0xbfb8aa3b, v129
	v_lshlrev_b64 v[204:205], 12, v[122:123]
	v_lshlrev_b64 v[236:237], 12, v[124:125]
	v_lshl_add_u64 v[184:185], v[132:133], 0, s[22:23]
	s_mov_b64 s[22:23], 0xb0000
	v_lshl_add_u64 v[138:139], v[134:135], 0, v[202:203]
	v_exp_f32_e32 v209, v126
	v_exp_f32_e32 v242, v127
	v_lshl_add_u64 v[122:123], v[134:135], 0, v[204:205]
	v_exp_f32_e32 v243, v128
	v_exp_f32_e32 v244, v129
	v_lshl_add_u64 v[182:183], v[132:133], 0, s[22:23]
	v_lshl_add_u64 v[124:125], v[134:135], 0, v[236:237]
	v_lshl_add_u64 v[126:127], v[134:135], 0, v[234:235]
	v_lshl_add_u64 v[128:129], v[134:135], 0, v[238:239]
	global_load_dwordx4 v[214:217], v[138:139], off
	global_load_dwordx4 v[218:221], v[122:123], off
	v_exp_f32_e32 v245, v131
	v_exp_f32_e32 v246, v140
	v_exp_f32_e32 v247, v141
	v_lshl_add_u64 v[240:241], s[26:27], 0, v[132:133]
	v_lshl_add_u64 v[130:131], v[134:135], 0, v[184:185]
	v_lshl_add_u64 v[132:133], v[134:135], 0, v[182:183]
	global_load_dwordx4 v[158:161], v[136:137], off offset:256
	global_load_dwordx4 v[154:157], v[138:139], off offset:256
	global_load_dwordx4 v[146:149], v[122:123], off offset:256
	global_load_dwordx4 v[222:225], v[124:125], off
	global_load_dwordx4 v[142:145], v[124:125], off offset:256
	global_load_dwordx4 v[226:229], v[126:127], off
	s_nop 0
	global_load_dwordx4 v[138:141], v[126:127], off offset:256
	global_load_dwordx4 v[230:233], v[128:129], off
	global_load_dwordx4 v[134:137], v[128:129], off offset:256
	global_load_dwordx4 v[166:169], v[130:131], off
	s_nop 0
	global_load_dwordx4 v[126:129], v[130:131], off offset:256
	global_load_dwordx4 v[162:165], v[132:133], off
	global_load_dwordx4 v[122:125], v[132:133], off offset:256
	v_add_f32_e32 v130, 1.0, v209
	v_add_f32_e32 v131, 1.0, v242
	v_add_f32_e32 v132, 1.0, v243
	v_add_f32_e32 v133, 1.0, v244
	v_add_f32_e32 v209, 1.0, v245
	v_rcp_f32_e32 v242, v130
	v_rcp_f32_e32 v243, v131
	v_rcp_f32_e32 v244, v132
	v_rcp_f32_e32 v245, v133
	global_load_dwordx4 v[130:133], v[190:191], off offset:256
	v_mul_f32_e32 v54, 0xbfb8aa3b, v54
	v_mul_f32_e32 v55, 0xbfb8aa3b, v55
	v_mul_f32_e32 v56, 0xbfb8aa3b, v56
	v_mul_f32_e32 v57, 0xbfb8aa3b, v57
	v_exp_f32_e32 v54, v54
	v_exp_f32_e32 v55, v55
	v_exp_f32_e32 v56, v56
	v_exp_f32_e32 v57, v57
	v_mul_f32_e32 v48, 0xbfb8aa3b, v48
	v_add_f32_e32 v54, 1.0, v54
	v_add_f32_e32 v55, 1.0, v55
	v_add_f32_e32 v56, 1.0, v56
	v_add_f32_e32 v57, 1.0, v57
	v_mul_f32_e32 v46, 0xbfb8aa3b, v46
	v_mul_f32_e32 v47, 0xbfb8aa3b, v47
	v_exp_f32_e32 v48, v48
	v_mul_f32_e32 v49, 0xbfb8aa3b, v49
	v_rcp_f32_e32 v54, v54
	v_rcp_f32_e32 v55, v55
	v_rcp_f32_e32 v56, v56
	v_rcp_f32_e32 v57, v57
	v_exp_f32_e32 v46, v46
	v_exp_f32_e32 v47, v47
	v_exp_f32_e32 v49, v49
	v_mul_f32_e32 v88, 0xbfb8aa3b, v88
	v_mul_f32_e32 v89, 0xbfb8aa3b, v89
	v_exp_f32_e32 v88, v88
	v_exp_f32_e32 v89, v89
	v_mul_f32_e32 v80, 0xbfb8aa3b, v80
	v_mul_f32_e32 v81, 0xbfb8aa3b, v81
	v_exp_f32_e32 v80, v80
	v_exp_f32_e32 v81, v81
	v_add_f32_e32 v48, 1.0, v48
	v_mul_f32_e32 v40, 0xbfb8aa3b, v40
	v_pk_mul_f32 v[54:55], v[50:51], v[54:55]
	v_pk_mul_f32 v[50:51], v[52:53], v[56:57]
	v_add_f32_e32 v46, 1.0, v46
	v_add_f32_e32 v47, 1.0, v47
	v_rcp_f32_e32 v52, v48
	v_add_f32_e32 v48, 1.0, v49
	v_mul_f32_e32 v38, 0xbfb8aa3b, v38
	v_mul_f32_e32 v39, 0xbfb8aa3b, v39
	v_exp_f32_e32 v40, v40
	v_mul_f32_e32 v41, 0xbfb8aa3b, v41
	v_rcp_f32_e32 v46, v46
	v_rcp_f32_e32 v47, v47
	v_rcp_f32_e32 v53, v48
	v_exp_f32_e32 v38, v38
	v_exp_f32_e32 v39, v39
	v_exp_f32_e32 v41, v41
	v_add_f32_e32 v88, 1.0, v88
	v_add_f32_e32 v89, 1.0, v89
	v_rcp_f32_e32 v88, v88
	v_rcp_f32_e32 v89, v89
	v_add_f32_e32 v80, 1.0, v80
	v_add_f32_e32 v81, 1.0, v81
	v_rcp_f32_e32 v80, v80
	v_rcp_f32_e32 v81, v81
	v_add_f32_e32 v40, 1.0, v40
	v_mul_f32_e32 v32, 0xbfb8aa3b, v32
	v_pk_mul_f32 v[46:47], v[42:43], v[46:47]
	v_pk_mul_f32 v[42:43], v[44:45], v[52:53]
	v_add_f32_e32 v38, 1.0, v38
	v_add_f32_e32 v39, 1.0, v39
	v_rcp_f32_e32 v44, v40
	v_add_f32_e32 v40, 1.0, v41
	v_mul_f32_e32 v30, 0xbfb8aa3b, v30
	v_mul_f32_e32 v31, 0xbfb8aa3b, v31
	v_exp_f32_e32 v32, v32
	v_mul_f32_e32 v33, 0xbfb8aa3b, v33
	v_mul_f32_e32 v78, 0xbfb8aa3b, v78
	v_rcp_f32_e32 v38, v38
	v_rcp_f32_e32 v39, v39
	v_rcp_f32_e32 v45, v40
	v_exp_f32_e32 v30, v30
	v_exp_f32_e32 v31, v31
	v_exp_f32_e32 v33, v33
	v_pk_mul_f32 v[84:85], v[84:85], v[88:89]
	v_exp_f32_e32 v88, v78
	v_mul_f32_e32 v78, 0xbfb8aa3b, v79
	v_mul_f32_e32 v62, 0xbfb8aa3b, v62
	v_exp_f32_e32 v89, v78
	v_pk_mul_f32 v[76:77], v[76:77], v[80:81]
	v_exp_f32_e32 v80, v62
	v_mul_f32_e32 v62, 0xbfb8aa3b, v63
	v_exp_f32_e32 v81, v62
	v_mul_f32_e32 v64, 0xbfb8aa3b, v64
	v_mul_f32_e32 v65, 0xbfb8aa3b, v65
	v_add_f32_e32 v32, 1.0, v32
	v_mul_f32_e32 v24, 0xbfb8aa3b, v24
	v_mul_f32_e32 v112, 0xbfb8aa3b, v112
	v_mul_f32_e32 v113, 0xbfb8aa3b, v113
	v_mul_f32_e32 v104, 0xbfb8aa3b, v104
	v_mul_f32_e32 v105, 0xbfb8aa3b, v105
	v_mul_f32_e32 v96, 0xbfb8aa3b, v96
	v_mul_f32_e32 v97, 0xbfb8aa3b, v97
	v_exp_f32_e32 v64, v64
	v_exp_f32_e32 v65, v65
	v_pk_mul_f32 v[38:39], v[34:35], v[38:39]
	v_pk_mul_f32 v[34:35], v[36:37], v[44:45]
	v_add_f32_e32 v30, 1.0, v30
	v_add_f32_e32 v31, 1.0, v31
	v_rcp_f32_e32 v36, v32
	v_add_f32_e32 v32, 1.0, v33
	v_mul_f32_e32 v22, 0xbfb8aa3b, v22
	v_mul_f32_e32 v23, 0xbfb8aa3b, v23
	v_exp_f32_e32 v24, v24
	v_mul_f32_e32 v25, 0xbfb8aa3b, v25
	v_exp_f32_e32 v112, v112
	v_exp_f32_e32 v113, v113
	v_exp_f32_e32 v104, v104
	v_exp_f32_e32 v105, v105
	v_exp_f32_e32 v96, v96
	v_exp_f32_e32 v97, v97
	v_rcp_f32_e32 v30, v30
	v_rcp_f32_e32 v31, v31
	v_rcp_f32_e32 v37, v32
	v_exp_f32_e32 v22, v22
	v_exp_f32_e32 v23, v23
	v_exp_f32_e32 v25, v25
	v_add_f32_e32 v88, 1.0, v88
	v_add_f32_e32 v89, 1.0, v89
	v_rcp_f32_e32 v88, v88
	v_rcp_f32_e32 v89, v89
	v_add_f32_e32 v80, 1.0, v80
	v_add_f32_e32 v81, 1.0, v81
	v_pk_mul_f32 v[118:119], v[118:119], v[242:243]
	v_rcp_f32_e32 v80, v80
	v_rcp_f32_e32 v81, v81
	v_add_f32_e32 v64, 1.0, v64
	v_add_f32_e32 v65, 1.0, v65
	v_add_f32_e32 v24, 1.0, v24
	v_mul_f32_e32 v16, 0xbfb8aa3b, v16
	v_add_f32_e32 v250, 1.0, v247
	v_pk_mul_f32 v[120:121], v[120:121], v[244:245]
	s_waitcnt vmcnt(0)
	v_pk_fma_f32 v[210:211], v[118:119], v[150:151], v[210:211]
	v_add_f32_e32 v118, 1.0, v248
	v_add_f32_e32 v112, 1.0, v112
	v_add_f32_e32 v113, 1.0, v113
	v_add_f32_e32 v104, 1.0, v104
	v_add_f32_e32 v105, 1.0, v105
	v_add_f32_e32 v96, 1.0, v96
	v_add_f32_e32 v97, 1.0, v97
	v_rcp_f32_e32 v64, v64
	v_rcp_f32_e32 v65, v65
	v_pk_mul_f32 v[30:31], v[26:27], v[30:31]
	v_pk_mul_f32 v[26:27], v[28:29], v[36:37]
	v_add_f32_e32 v22, 1.0, v22
	v_add_f32_e32 v23, 1.0, v23
	v_rcp_f32_e32 v28, v24
	v_add_f32_e32 v24, 1.0, v25
	v_mul_f32_e32 v14, 0xbfb8aa3b, v14
	v_mul_f32_e32 v15, 0xbfb8aa3b, v15
	v_exp_f32_e32 v16, v16
	v_mul_f32_e32 v17, 0xbfb8aa3b, v17
	v_pk_fma_f32 v[212:213], v[120:121], v[152:153], v[212:213]
	v_rcp_f32_e32 v120, v250
	v_rcp_f32_e32 v121, v118
	v_rcp_f32_e32 v112, v112
	v_rcp_f32_e32 v113, v113
	v_rcp_f32_e32 v104, v104
	v_rcp_f32_e32 v105, v105
	v_rcp_f32_e32 v96, v96
	v_rcp_f32_e32 v97, v97
	v_rcp_f32_e32 v22, v22
	v_rcp_f32_e32 v23, v23
	v_rcp_f32_e32 v29, v24
	v_exp_f32_e32 v14, v14
	v_exp_f32_e32 v15, v15
	v_exp_f32_e32 v17, v17
	v_pk_mul_f32 v[74:75], v[74:75], v[88:89]
	v_lshl_add_u64 v[62:63], s[26:27], 0, v[184:185]
	v_pk_fma_f32 v[76:77], v[76:77], v[152:153], v[168:169]
	v_pk_fma_f32 v[74:75], v[74:75], v[150:151], v[166:167]
	v_lshl_add_u64 v[62:63], v[62:63], 0, v[180:181]
	v_pk_mul_f32 v[58:59], v[58:59], v[80:81]
	v_mul_f32_e32 v110, 0xbfb8aa3b, v110
	v_mul_f32_e32 v102, 0xbfb8aa3b, v102
	v_mul_f32_e32 v94, 0xbfb8aa3b, v94
	v_mul_f32_e32 v86, 0xbfb8aa3b, v86
	global_store_dwordx4 v[62:63], v[74:77], off
	v_pk_mul_f32 v[60:61], v[60:61], v[64:65]
	v_add_f32_e32 v16, 1.0, v16
	v_pk_fma_f32 v[74:75], v[58:59], v[150:151], v[162:163]
	v_mul_f32_e32 v58, 0xbfb8aa3b, v70
	v_mul_f32_e32 v8, 0xbfb8aa3b, v8
	v_pk_mul_f32 v[116:117], v[116:117], v[120:121]
	v_exp_f32_e32 v120, v110
	v_mul_f32_e32 v110, 0xbfb8aa3b, v111
	v_pk_mul_f32 v[108:109], v[108:109], v[112:113]
	v_exp_f32_e32 v112, v102
	v_mul_f32_e32 v102, 0xbfb8aa3b, v103
	v_pk_mul_f32 v[100:101], v[100:101], v[104:105]
	v_exp_f32_e32 v104, v94
	v_mul_f32_e32 v94, 0xbfb8aa3b, v95
	v_pk_mul_f32 v[92:93], v[92:93], v[96:97]
	v_exp_f32_e32 v96, v86
	v_mul_f32_e32 v86, 0xbfb8aa3b, v87
	v_pk_fma_f32 v[76:77], v[60:61], v[152:153], v[164:165]
	v_exp_f32_e32 v60, v58
	v_mul_f32_e32 v58, 0xbfb8aa3b, v71
	v_mul_f32_e32 v64, 0xbfb8aa3b, v72
	v_mul_f32_e32 v65, 0xbfb8aa3b, v73
	v_pk_mul_f32 v[22:23], v[18:19], v[22:23]
	v_pk_mul_f32 v[18:19], v[20:21], v[28:29]
	v_add_f32_e32 v14, 1.0, v14
	v_add_f32_e32 v15, 1.0, v15
	v_rcp_f32_e32 v20, v16
	v_add_f32_e32 v16, 1.0, v17
	v_mul_f32_e32 v6, 0xbfb8aa3b, v6
	v_mul_f32_e32 v7, 0xbfb8aa3b, v7
	v_exp_f32_e32 v8, v8
	v_mul_f32_e32 v9, 0xbfb8aa3b, v9
	v_exp_f32_e32 v121, v110
	v_exp_f32_e32 v113, v102
	v_exp_f32_e32 v105, v94
	v_exp_f32_e32 v97, v86
	v_exp_f32_e32 v61, v58
	v_exp_f32_e32 v64, v64
	v_exp_f32_e32 v65, v65
	v_rcp_f32_e32 v14, v14
	v_rcp_f32_e32 v15, v15
	v_rcp_f32_e32 v21, v16
	v_exp_f32_e32 v6, v6
	v_exp_f32_e32 v7, v7
	v_exp_f32_e32 v9, v9
	v_add_f32_e32 v8, 1.0, v8
	v_add_f32_e32 v249, 1.0, v246
	v_add_f32_e32 v120, 1.0, v120
	v_add_f32_e32 v121, 1.0, v121
	v_add_f32_e32 v112, 1.0, v112
	v_add_f32_e32 v113, 1.0, v113
	v_add_f32_e32 v104, 1.0, v104
	v_add_f32_e32 v105, 1.0, v105
	v_add_f32_e32 v96, 1.0, v96
	v_add_f32_e32 v97, 1.0, v97
	v_add_f32_e32 v60, 1.0, v60
	v_add_f32_e32 v61, 1.0, v61
	v_add_f32_e32 v64, 1.0, v64
	v_add_f32_e32 v65, 1.0, v65
	v_pk_mul_f32 v[14:15], v[10:11], v[14:15]
	v_pk_mul_f32 v[10:11], v[12:13], v[20:21]
	v_add_f32_e32 v6, 1.0, v6
	v_add_f32_e32 v7, 1.0, v7
	v_rcp_f32_e32 v12, v8
	v_add_f32_e32 v8, 1.0, v9
	v_rcp_f32_e32 v246, v209
	v_rcp_f32_e32 v247, v249
	v_rcp_f32_e32 v120, v120
	v_rcp_f32_e32 v121, v121
	v_rcp_f32_e32 v112, v112
	v_rcp_f32_e32 v113, v113
	v_rcp_f32_e32 v104, v104
	v_rcp_f32_e32 v105, v105
	v_rcp_f32_e32 v96, v96
	v_rcp_f32_e32 v97, v97
	v_rcp_f32_e32 v60, v60
	v_rcp_f32_e32 v61, v61
	v_rcp_f32_e32 v64, v64
	v_rcp_f32_e32 v65, v65
	v_rcp_f32_e32 v6, v6
	v_rcp_f32_e32 v7, v7
	v_rcp_f32_e32 v13, v8
	v_pk_mul_f32 v[114:115], v[114:115], v[246:247]
	v_lshl_add_u64 v[110:111], s[26:27], 0, v[202:203]
	v_pk_mul_f32 v[106:107], v[106:107], v[120:121]
	v_lshl_add_u64 v[102:103], s[26:27], 0, v[204:205]
	v_pk_mul_f32 v[98:99], v[98:99], v[112:113]
	v_lshl_add_u64 v[94:95], s[26:27], 0, v[236:237]
	v_pk_mul_f32 v[90:91], v[90:91], v[104:105]
	v_lshl_add_u64 v[86:87], s[26:27], 0, v[234:235]
	v_pk_mul_f32 v[82:83], v[82:83], v[96:97]
	v_lshl_add_u64 v[78:79], s[26:27], 0, v[238:239]
	v_lshl_add_u64 v[58:59], s[26:27], 0, v[182:183]
	v_pk_mul_f32 v[60:61], v[66:67], v[60:61]
	v_pk_mul_f32 v[64:65], v[68:69], v[64:65]
	v_pk_mul_f32 v[2:3], v[2:3], v[6:7]
	v_pk_mul_f32 v[4:5], v[4:5], v[12:13]
	v_lshl_add_u64 v[118:119], v[240:241], 0, v[180:181]
	v_pk_fma_f32 v[116:117], v[116:117], v[152:153], v[216:217]
	v_pk_fma_f32 v[114:115], v[114:115], v[150:151], v[214:215]
	v_lshl_add_u64 v[110:111], v[110:111], 0, v[180:181]
	v_pk_fma_f32 v[108:109], v[108:109], v[152:153], v[220:221]
	v_pk_fma_f32 v[106:107], v[106:107], v[150:151], v[218:219]
	v_lshl_add_u64 v[102:103], v[102:103], 0, v[180:181]
	v_pk_fma_f32 v[100:101], v[100:101], v[152:153], v[224:225]
	v_pk_fma_f32 v[98:99], v[98:99], v[150:151], v[222:223]
	v_lshl_add_u64 v[94:95], v[94:95], 0, v[180:181]
	v_pk_fma_f32 v[92:93], v[92:93], v[152:153], v[228:229]
	v_pk_fma_f32 v[90:91], v[90:91], v[150:151], v[226:227]
	v_lshl_add_u64 v[86:87], v[86:87], 0, v[180:181]
	v_pk_fma_f32 v[84:85], v[84:85], v[152:153], v[232:233]
	v_pk_fma_f32 v[82:83], v[82:83], v[150:151], v[230:231]
	v_lshl_add_u64 v[78:79], v[78:79], 0, v[180:181]
	v_lshl_add_u64 v[58:59], v[58:59], 0, v[180:181]
	v_pk_fma_f32 v[66:67], v[64:65], v[132:133], v[160:161]
	v_pk_fma_f32 v[64:65], v[60:61], v[130:131], v[158:159]
	v_pk_fma_f32 v[50:51], v[50:51], v[132:133], v[156:157]
	v_pk_fma_f32 v[48:49], v[54:55], v[130:131], v[154:155]
	v_pk_fma_f32 v[42:43], v[42:43], v[132:133], v[148:149]
	v_pk_fma_f32 v[40:41], v[46:47], v[130:131], v[146:147]
	v_pk_fma_f32 v[34:35], v[34:35], v[132:133], v[144:145]
	v_pk_fma_f32 v[32:33], v[38:39], v[130:131], v[142:143]
	v_pk_fma_f32 v[26:27], v[26:27], v[132:133], v[140:141]
	v_pk_fma_f32 v[24:25], v[30:31], v[130:131], v[138:139]
	v_pk_fma_f32 v[18:19], v[18:19], v[132:133], v[136:137]
	v_pk_fma_f32 v[16:17], v[22:23], v[130:131], v[134:135]
	v_pk_fma_f32 v[10:11], v[10:11], v[132:133], v[128:129]
	v_pk_fma_f32 v[8:9], v[14:15], v[130:131], v[126:127]
	v_pk_fma_f32 v[4:5], v[4:5], v[132:133], v[124:125]
	v_pk_fma_f32 v[2:3], v[2:3], v[130:131], v[122:123]
	s_and_b64 vcc, exec, s[2:3]
	s_mov_b32 s66, s0
	s_mov_b32 s67, s4
	s_mov_b64 s[54:55], s[18:19]
	s_mov_b64 s[52:53], s[6:7]
	global_store_dwordx4 v[118:119], v[210:213], off
	global_store_dwordx4 v[110:111], v[114:117], off
	global_store_dwordx4 v[102:103], v[106:109], off
	global_store_dwordx4 v[94:95], v[98:101], off
	global_store_dwordx4 v[86:87], v[90:93], off
	global_store_dwordx4 v[78:79], v[82:85], off
	global_store_dwordx4 v[58:59], v[74:77], off
	global_store_dwordx4 v[118:119], v[64:67], off offset:256
	global_store_dwordx4 v[110:111], v[48:51], off offset:256
	global_store_dwordx4 v[102:103], v[40:43], off offset:256
	global_store_dwordx4 v[94:95], v[32:35], off offset:256
	global_store_dwordx4 v[86:87], v[24:27], off offset:256
	global_store_dwordx4 v[78:79], v[16:19], off offset:256
	global_store_dwordx4 v[62:63], v[8:11], off offset:256
	global_store_dwordx4 v[58:59], v[2:5], off offset:256
	s_cbranch_vccz .LBB0_419
	s_waitcnt vmcnt(0)
	v_readlane_b32 s66, v252, 44
	v_readlane_b32 s64, v254, 62
	s_cmpk_gt_u32 s14, 0xff
	v_readlane_b32 s67, v252, 45
	v_readlane_b32 s65, v254, 63
	s_cbranch_scc1 .LBB0_426
	s_barrier

.LBB0_490:
	s_add_u32 s52, s0, 0xfffc0080
	s_addc_u32 s53, s1, -1
	s_add_i32 s68, 0, 0x10000
	v_add_u32_e32 v0, s68, v168
	ds_read_b128 v[122:125], v0
	ds_read_b128 v[126:129], v0 offset:1024
	ds_read_b128 v[134:137], v0 offset:2048
	ds_read_b128 v[138:141], v0 offset:3072
	s_cmp_eq_u32 s23, 12
	s_cselect_b32 s63, s19, s53
	s_cselect_b32 s62, s67, s52
	s_cselect_b32 s53, s55, s22
	s_cselect_b32 s52, vcc_lo, vcc_hi
	v_lshl_add_u64 v[190:191], s[0:1], 0, v[152:153]
	s_add_i32 m0, s21, 0xc000
	ds_read_b128 v[156:159], v169
	ds_read_b128 v[160:163], v169 offset:1024
	ds_read_b128 v[164:167], v169 offset:2048
	ds_read_b128 v[170:173], v169 offset:3072
	ds_read_b128 v[178:181], v169 offset:4096
	ds_read_b128 v[182:185], v169 offset:5120
	ds_read_b128 v[186:189], v169 offset:6144
	ds_read_b128 v[210:213], v169 offset:7168
	global_load_lds_dwordx4 v[190:191], off
	v_lshl_add_u64 v[190:191], s[0:1], 0, v[154:155]
	s_add_i32 m0, s21, 0xe000
	s_nop 0
	global_load_lds_dwordx4 v[190:191], off
	s_waitcnt lgkmcnt(8)
	s_barrier
	s_waitcnt lgkmcnt(0)


	v_mfma_f32_16x16x32_bf16 v[142:145], v[122:125], v[156:159], v[142:145]
	v_mfma_f32_16x16x32_bf16 v[130:133], v[134:137], v[156:159], v[130:133]
	v_mfma_f32_16x16x32_bf16 v[110:113], v[122:125], v[164:167], v[110:113]
	v_mfma_f32_16x16x32_bf16 v[106:109], v[134:137], v[164:167], v[106:109]
	v_mfma_f32_16x16x32_bf16 v[94:97], v[122:125], v[178:181], v[94:97]
	v_mfma_f32_16x16x32_bf16 v[90:93], v[134:137], v[178:181], v[90:93]
	v_mfma_f32_16x16x32_bf16 v[78:81], v[122:125], v[186:189], v[78:81]
	v_mfma_f32_16x16x32_bf16 v[74:77], v[134:137], v[186:189], v[74:77]
	v_mfma_f32_16x16x32_bf16 v[142:145], v[126:129], v[160:163], v[142:145]
	v_mfma_f32_16x16x32_bf16 v[130:133], v[138:141], v[160:163], v[130:133]
	v_mfma_f32_16x16x32_bf16 v[110:113], v[126:129], v[170:173], v[110:113]
	v_mfma_f32_16x16x32_bf16 v[106:109], v[138:141], v[170:173], v[106:109]
	v_mfma_f32_16x16x32_bf16 v[94:97], v[126:129], v[182:185], v[94:97]
	v_mfma_f32_16x16x32_bf16 v[90:93], v[138:141], v[182:185], v[90:93]
	v_mfma_f32_16x16x32_bf16 v[78:81], v[126:129], v[210:213], v[78:81]
	v_mfma_f32_16x16x32_bf16 v[74:77], v[138:141], v[210:213], v[74:77]

	s_barrier
	s_add_i32 s70, 0, 0x14000
	s_add_i32 s68, s68, s20
	v_add_u32_e32 v0, s70, v168
	v_lshl_add_u64 v[190:191], s[52:53], 0, v[148:149]
	s_mov_b32 m0, s68
	ds_read_b128 v[214:217], v0
	ds_read_b128 v[218:221], v0 offset:1024
	ds_read_b128 v[222:225], v0 offset:2048
	ds_read_b128 v[226:229], v0 offset:3072
	global_load_lds_dwordx4 v[190:191], off
	v_lshl_add_u64 v[202:203], s[52:53], 0, v[146:147]
	s_add_i32 m0, s68, 0x2000
	s_nop 0
	global_load_lds_dwordx4 v[202:203], off
	s_barrier
	s_waitcnt lgkmcnt(0)


	v_mfma_f32_16x16x32_bf16 v[118:121], v[214:217], v[156:159], v[118:121]
	v_mfma_f32_16x16x32_bf16 v[114:117], v[222:225], v[156:159], v[114:117]
	v_mfma_f32_16x16x32_bf16 v[102:105], v[214:217], v[164:167], v[102:105]
	v_mfma_f32_16x16x32_bf16 v[98:101], v[222:225], v[164:167], v[98:101]
	v_mfma_f32_16x16x32_bf16 v[86:89], v[214:217], v[178:181], v[86:89]
	v_mfma_f32_16x16x32_bf16 v[82:85], v[222:225], v[178:181], v[82:85]
	v_mfma_f32_16x16x32_bf16 v[70:73], v[214:217], v[186:189], v[70:73]
	v_mfma_f32_16x16x32_bf16 v[66:69], v[222:225], v[186:189], v[66:69]
	v_mfma_f32_16x16x32_bf16 v[118:121], v[218:221], v[160:163], v[118:121]
	v_mfma_f32_16x16x32_bf16 v[114:117], v[226:229], v[160:163], v[114:117]
	v_mfma_f32_16x16x32_bf16 v[102:105], v[218:221], v[170:173], v[102:105]
	v_mfma_f32_16x16x32_bf16 v[98:101], v[226:229], v[170:173], v[98:101]
	v_mfma_f32_16x16x32_bf16 v[86:89], v[218:221], v[182:185], v[86:89]
	v_mfma_f32_16x16x32_bf16 v[82:85], v[226:229], v[182:185], v[82:85]
	v_mfma_f32_16x16x32_bf16 v[70:73], v[218:221], v[210:213], v[70:73]
	v_mfma_f32_16x16x32_bf16 v[66:69], v[226:229], v[210:213], v[66:69]

	s_mov_b32 m0, s21
	v_lshl_add_u64 v[204:205], s[62:63], 0, v[148:149]
	s_barrier
	ds_read_b128 v[156:159], v169 offset:16384
	ds_read_b128 v[160:163], v169 offset:17408
	ds_read_b128 v[164:167], v169 offset:18432
	ds_read_b128 v[170:173], v169 offset:19456
	ds_read_b128 v[178:181], v169 offset:20480
	ds_read_b128 v[182:185], v169 offset:21504
	ds_read_b128 v[186:189], v169 offset:22528
	ds_read_b128 v[210:213], v169 offset:23552
	global_load_lds_dwordx4 v[204:205], off
	v_lshl_add_u64 v[230:231], s[62:63], 0, v[146:147]
	s_mov_b32 m0, s40
	s_nop 0
	global_load_lds_dwordx4 v[230:231], off
	s_barrier
	s_waitcnt lgkmcnt(0)


	v_mfma_f32_16x16x32_bf16 v[62:65], v[122:125], v[156:159], v[62:65]
	v_mfma_f32_16x16x32_bf16 v[58:61], v[134:137], v[156:159], v[58:61]
	v_mfma_f32_16x16x32_bf16 v[46:49], v[122:125], v[164:167], v[46:49]
	v_mfma_f32_16x16x32_bf16 v[42:45], v[134:137], v[164:167], v[42:45]
	v_mfma_f32_16x16x32_bf16 v[30:33], v[122:125], v[178:181], v[30:33]
	v_mfma_f32_16x16x32_bf16 v[26:29], v[134:137], v[178:181], v[26:29]
	v_mfma_f32_16x16x32_bf16 v[14:17], v[122:125], v[186:189], v[14:17]
	v_mfma_f32_16x16x32_bf16 v[10:13], v[134:137], v[186:189], v[10:13]
	v_mfma_f32_16x16x32_bf16 v[62:65], v[126:129], v[160:163], v[62:65]
	v_mfma_f32_16x16x32_bf16 v[58:61], v[138:141], v[160:163], v[58:61]
	v_mfma_f32_16x16x32_bf16 v[46:49], v[126:129], v[170:173], v[46:49]
	v_mfma_f32_16x16x32_bf16 v[42:45], v[138:141], v[170:173], v[42:45]
	v_mfma_f32_16x16x32_bf16 v[30:33], v[126:129], v[182:185], v[30:33]
	v_mfma_f32_16x16x32_bf16 v[26:29], v[138:141], v[182:185], v[26:29]
	v_mfma_f32_16x16x32_bf16 v[14:17], v[126:129], v[210:213], v[14:17]
	v_mfma_f32_16x16x32_bf16 v[10:13], v[138:141], v[210:213], v[10:13]

	s_barrier
	s_add_u32 s68, s52, 0x40000
	s_addc_u32 s69, s53, 0
	s_add_i32 s70, s70, s20
	v_lshl_add_u64 v[122:123], s[68:69], 0, v[148:149]
	s_mov_b32 m0, s70
	s_nop 0
	global_load_lds_dwordx4 v[122:123], off
	v_lshl_add_u64 v[122:123], s[68:69], 0, v[146:147]
	s_add_i32 m0, s70, 0x2000
	s_nop 0
	global_load_lds_dwordx4 v[122:123], off
	s_waitcnt vmcnt(6)
	s_barrier

	v_mfma_f32_16x16x32_bf16 v[54:57], v[214:217], v[156:159], v[54:57]
	v_mfma_f32_16x16x32_bf16 v[50:53], v[222:225], v[156:159], v[50:53]
	v_mfma_f32_16x16x32_bf16 v[38:41], v[214:217], v[164:167], v[38:41]
	v_mfma_f32_16x16x32_bf16 v[34:37], v[222:225], v[164:167], v[34:37]
	v_mfma_f32_16x16x32_bf16 v[22:25], v[214:217], v[178:181], v[22:25]
	v_mfma_f32_16x16x32_bf16 v[18:21], v[222:225], v[178:181], v[18:21]
	v_mfma_f32_16x16x32_bf16 v[6:9], v[214:217], v[186:189], v[6:9]
	v_mfma_f32_16x16x32_bf16 v[2:5], v[222:225], v[186:189], v[2:5]
	v_mfma_f32_16x16x32_bf16 v[54:57], v[218:221], v[160:163], v[54:57]
	v_mfma_f32_16x16x32_bf16 v[50:53], v[226:229], v[160:163], v[50:53]
	v_mfma_f32_16x16x32_bf16 v[38:41], v[218:221], v[170:173], v[38:41]
	v_mfma_f32_16x16x32_bf16 v[34:37], v[226:229], v[170:173], v[34:37]
	v_mfma_f32_16x16x32_bf16 v[22:25], v[218:221], v[182:185], v[22:25]
	v_mfma_f32_16x16x32_bf16 v[18:21], v[226:229], v[182:185], v[18:21]
	v_mfma_f32_16x16x32_bf16 v[6:9], v[218:221], v[210:213], v[6:9]
	v_mfma_f32_16x16x32_bf16 v[2:5], v[226:229], v[210:213], v[2:5]

	s_add_i32 s68, 0, 0x18000
	v_add_u32_e32 v0, s68, v168
	s_barrier
	ds_read_b128 v[122:125], v0
	ds_read_b128 v[126:129], v0 offset:1024
	ds_read_b128 v[134:137], v0 offset:2048
	ds_read_b128 v[138:141], v0 offset:3072
	s_add_u32 s62, s62, 0x40000
	s_addc_u32 s63, s63, 0
	s_mov_b32 m0, s41
	v_lshl_add_u64 v[214:215], s[62:63], 0, v[148:149]
	ds_read_b128 v[156:159], v169 offset:32768
	ds_read_b128 v[160:163], v169 offset:33792
	ds_read_b128 v[164:167], v169 offset:34816
	ds_read_b128 v[170:173], v169 offset:35840
	ds_read_b128 v[178:181], v169 offset:36864
	ds_read_b128 v[182:185], v169 offset:37888
	ds_read_b128 v[186:189], v169 offset:38912
	ds_read_b128 v[210:213], v169 offset:39936
	global_load_lds_dwordx4 v[214:215], off
	v_lshl_add_u64 v[214:215], s[62:63], 0, v[146:147]
	s_mov_b32 m0, s42
	s_nop 0
	global_load_lds_dwordx4 v[214:215], off
	s_waitcnt lgkmcnt(8)
	s_barrier
	s_waitcnt lgkmcnt(0)


	v_mfma_f32_16x16x32_bf16 v[142:145], v[122:125], v[156:159], v[142:145]
	v_mfma_f32_16x16x32_bf16 v[130:133], v[134:137], v[156:159], v[130:133]
	v_mfma_f32_16x16x32_bf16 v[110:113], v[122:125], v[164:167], v[110:113]
	v_mfma_f32_16x16x32_bf16 v[106:109], v[134:137], v[164:167], v[106:109]
	v_mfma_f32_16x16x32_bf16 v[94:97], v[122:125], v[178:181], v[94:97]
	v_mfma_f32_16x16x32_bf16 v[90:93], v[134:137], v[178:181], v[90:93]
	v_mfma_f32_16x16x32_bf16 v[78:81], v[122:125], v[186:189], v[78:81]
	v_mfma_f32_16x16x32_bf16 v[74:77], v[134:137], v[186:189], v[74:77]
	v_mfma_f32_16x16x32_bf16 v[142:145], v[126:129], v[160:163], v[142:145]
	v_mfma_f32_16x16x32_bf16 v[130:133], v[138:141], v[160:163], v[130:133]
	v_mfma_f32_16x16x32_bf16 v[110:113], v[126:129], v[170:173], v[110:113]
	v_mfma_f32_16x16x32_bf16 v[106:109], v[138:141], v[170:173], v[106:109]
	v_mfma_f32_16x16x32_bf16 v[94:97], v[126:129], v[182:185], v[94:97]
	v_mfma_f32_16x16x32_bf16 v[90:93], v[138:141], v[182:185], v[90:93]
	v_mfma_f32_16x16x32_bf16 v[78:81], v[126:129], v[210:213], v[78:81]
	v_mfma_f32_16x16x32_bf16 v[74:77], v[138:141], v[210:213], v[74:77]

	s_barrier
	s_add_i32 s62, 0, 0x1c000
	s_add_i32 s63, s68, s20
	v_add_u32_e32 v0, s62, v168
	v_lshl_add_u64 v[190:191], v[190:191], 0, s[60:61]
	s_mov_b32 m0, s63
	ds_read_b128 v[214:217], v0
	ds_read_b128 v[218:221], v0 offset:1024
	ds_read_b128 v[222:225], v0 offset:2048
	ds_read_b128 v[226:229], v0 offset:3072
	global_load_lds_dwordx4 v[190:191], off
	v_lshl_add_u64 v[190:191], v[202:203], 0, s[60:61]
	s_add_i32 m0, s63, 0x2000
	s_nop 0
	global_load_lds_dwordx4 v[190:191], off
	s_barrier
	s_waitcnt lgkmcnt(0)


	v_mfma_f32_16x16x32_bf16 v[118:121], v[214:217], v[156:159], v[118:121]
	v_mfma_f32_16x16x32_bf16 v[114:117], v[222:225], v[156:159], v[114:117]
	v_mfma_f32_16x16x32_bf16 v[102:105], v[214:217], v[164:167], v[102:105]
	v_mfma_f32_16x16x32_bf16 v[98:101], v[222:225], v[164:167], v[98:101]
	v_mfma_f32_16x16x32_bf16 v[86:89], v[214:217], v[178:181], v[86:89]
	v_mfma_f32_16x16x32_bf16 v[82:85], v[222:225], v[178:181], v[82:85]
	v_mfma_f32_16x16x32_bf16 v[70:73], v[214:217], v[186:189], v[70:73]
	v_mfma_f32_16x16x32_bf16 v[66:69], v[222:225], v[186:189], v[66:69]
	v_mfma_f32_16x16x32_bf16 v[118:121], v[218:221], v[160:163], v[118:121]
	v_mfma_f32_16x16x32_bf16 v[114:117], v[226:229], v[160:163], v[114:117]
	v_mfma_f32_16x16x32_bf16 v[102:105], v[218:221], v[170:173], v[102:105]
	v_mfma_f32_16x16x32_bf16 v[98:101], v[226:229], v[170:173], v[98:101]
	v_mfma_f32_16x16x32_bf16 v[86:89], v[218:221], v[182:185], v[86:89]
	v_mfma_f32_16x16x32_bf16 v[82:85], v[226:229], v[182:185], v[82:85]
	v_mfma_f32_16x16x32_bf16 v[70:73], v[218:221], v[210:213], v[70:73]
	v_mfma_f32_16x16x32_bf16 v[66:69], v[226:229], v[210:213], v[66:69]

	s_mov_b32 m0, s95
	v_lshl_add_u64 v[190:191], v[204:205], 0, s[60:61]
	s_barrier
	ds_read_b128 v[156:159], v169 offset:49152
	ds_read_b128 v[160:163], v169 offset:50176
	ds_read_b128 v[164:167], v169 offset:51200
	ds_read_b128 v[170:173], v169 offset:52224
	ds_read_b128 v[178:181], v169 offset:53248
	ds_read_b128 v[182:185], v169 offset:54272
	ds_read_b128 v[186:189], v169 offset:55296
	ds_read_b128 v[210:213], v169 offset:56320
	global_load_lds_dwordx4 v[190:191], off
	v_lshl_add_u64 v[190:191], v[230:231], 0, s[60:61]
	s_mov_b32 m0, s96
	s_nop 0
	global_load_lds_dwordx4 v[190:191], off
	s_barrier
	s_waitcnt lgkmcnt(0)


	v_mfma_f32_16x16x32_bf16 v[62:65], v[122:125], v[156:159], v[62:65]
	v_mfma_f32_16x16x32_bf16 v[58:61], v[134:137], v[156:159], v[58:61]
	v_mfma_f32_16x16x32_bf16 v[46:49], v[122:125], v[164:167], v[46:49]
	v_mfma_f32_16x16x32_bf16 v[42:45], v[134:137], v[164:167], v[42:45]
	v_mfma_f32_16x16x32_bf16 v[30:33], v[122:125], v[178:181], v[30:33]
	v_mfma_f32_16x16x32_bf16 v[26:29], v[134:137], v[178:181], v[26:29]
	v_mfma_f32_16x16x32_bf16 v[14:17], v[122:125], v[186:189], v[14:17]
	v_mfma_f32_16x16x32_bf16 v[10:13], v[134:137], v[186:189], v[10:13]
	v_mfma_f32_16x16x32_bf16 v[62:65], v[126:129], v[160:163], v[62:65]
	v_mfma_f32_16x16x32_bf16 v[58:61], v[138:141], v[160:163], v[58:61]
	v_mfma_f32_16x16x32_bf16 v[46:49], v[126:129], v[170:173], v[46:49]
	v_mfma_f32_16x16x32_bf16 v[42:45], v[138:141], v[170:173], v[42:45]
	v_mfma_f32_16x16x32_bf16 v[30:33], v[126:129], v[182:185], v[30:33]
	v_mfma_f32_16x16x32_bf16 v[26:29], v[138:141], v[182:185], v[26:29]
	v_mfma_f32_16x16x32_bf16 v[14:17], v[126:129], v[210:213], v[14:17]
	v_mfma_f32_16x16x32_bf16 v[10:13], v[138:141], v[210:213], v[10:13]

	s_barrier
	s_add_u32 s52, s52, 0x40080
	s_addc_u32 s53, s53, 0
	s_add_i32 s62, s62, s20
	v_lshl_add_u64 v[122:123], s[52:53], 0, v[148:149]
	s_mov_b32 m0, s62
	s_nop 0
	global_load_lds_dwordx4 v[122:123], off
	v_lshl_add_u64 v[122:123], s[52:53], 0, v[146:147]
	s_add_i32 m0, s62, 0x2000
	s_nop 0
	global_load_lds_dwordx4 v[122:123], off
	s_waitcnt vmcnt(6)
	s_barrier

	v_mfma_f32_16x16x32_bf16 v[54:57], v[214:217], v[156:159], v[54:57]
	v_mfma_f32_16x16x32_bf16 v[50:53], v[222:225], v[156:159], v[50:53]
	v_mfma_f32_16x16x32_bf16 v[38:41], v[214:217], v[164:167], v[38:41]
	v_mfma_f32_16x16x32_bf16 v[34:37], v[222:225], v[164:167], v[34:37]
	v_mfma_f32_16x16x32_bf16 v[22:25], v[214:217], v[178:181], v[22:25]
	v_mfma_f32_16x16x32_bf16 v[18:21], v[222:225], v[178:181], v[18:21]
	v_mfma_f32_16x16x32_bf16 v[6:9], v[214:217], v[186:189], v[6:9]
	v_mfma_f32_16x16x32_bf16 v[2:5], v[222:225], v[186:189], v[2:5]
	v_mfma_f32_16x16x32_bf16 v[54:57], v[218:221], v[160:163], v[54:57]
	v_mfma_f32_16x16x32_bf16 v[50:53], v[226:229], v[160:163], v[50:53]
	v_mfma_f32_16x16x32_bf16 v[38:41], v[218:221], v[170:173], v[38:41]
	v_mfma_f32_16x16x32_bf16 v[34:37], v[226:229], v[170:173], v[34:37]
	v_mfma_f32_16x16x32_bf16 v[22:25], v[218:221], v[182:185], v[22:25]
	v_mfma_f32_16x16x32_bf16 v[18:21], v[226:229], v[182:185], v[18:21]
	v_mfma_f32_16x16x32_bf16 v[6:9], v[218:221], v[210:213], v[6:9]
	v_mfma_f32_16x16x32_bf16 v[2:5], v[226:229], v[210:213], v[2:5]

	s_add_i32 s23, s23, 2
	s_add_u32 s0, s0, 0x100
	s_addc_u32 s1, s1, 0
	s_add_u32 vcc_hi, vcc_hi, 0x100
	s_addc_u32 s22, s22, 0
	s_cmp_gt_u32 s23, 13
	s_barrier
	s_cbranch_scc0 .LBB0_490
	s_lshl_b32 s0, s14, 2
	s_lshl_b32 s19, s66, 8
	s_and_b32 s0, s0, 12
	s_add_i32 s19, s19, s94
	s_or_b32 s0, s0, s43
	v_or_b32_e32 v156, s19, v151
	s_ashr_i32 s55, s14, 2
	v_lshl_or_b32 v159, s0, 6, v150
	s_movk_i32 s22, 0x2000
	v_lshlrev_b32_e32 v122, 10, v156
	s_mov_b64 s[0:1], -1
	s_cmp_lt_i32 s55, 2
	v_ashrrev_i32_e32 v157, 31, v156
	v_cmp_gt_i32_e32 vcc, s22, v156
	v_lshlrev_b32_e32 v0, 1, v159
	v_and_b32_e32 v160, 0x33c00, v122
	s_cbranch_scc1 .LBB0_557
	s_ashr_i32 s0, s19, 8
	v_lshlrev_b64 v[122:123], 11, v[156:157]
	s_ashr_i32 s1, s0, 31
	v_lshl_add_u64 v[122:123], s[92:93], 0, v[122:123]
	s_lshl_b64 s[0:1], s[0:1], 21
	v_cvt_pk_bf16_f32 v126, v142, v143
	v_cvt_pk_bf16_f32 v127, v144, v145
	v_lshl_add_u64 v[124:125], v[122:123], 0, v[0:1]
	v_lshlrev_b32_e32 v122, 2, v160
	global_store_dwordx2 v[124:125], v[126:127], off
	s_and_saveexec_b64 s[52:53], vcc
	s_cbranch_execz .LBB0_494
	s_add_u32 s22, s6, s0
	s_addc_u32 s23, s7, s1
	v_mov_b32_e32 v123, v1
	v_lshl_add_u64 v[126:127], s[22:23], 0, v[122:123]
	v_lshlrev_b32_e32 v128, 2, v159
	v_mov_b32_e32 v129, v1
	v_lshl_add_u64 v[126:127], v[126:127], 0, v[128:129]
	global_store_dwordx4 v[126:127], v[142:145], off nt

.LBB0_801:
	s_add_u32 s54, s52, 0x100
	s_addc_u32 s55, s53, 0
	s_add_i32 s68, 0, 0x10000
	v_add_u32_e32 v122, s68, v210
	ds_read_b128 v[102:105], v122
	ds_read_b128 v[106:109], v122 offset:1024
	ds_read_b128 v[114:117], v122 offset:2048
	ds_read_b128 v[122:125], v122 offset:3072
	s_cmp_eq_u32 vcc_hi, 12
	s_cselect_b32 s59, s5, s55
	s_cselect_b32 s58, s14, s54
	s_cselect_b32 s57, s1, s23
	s_cselect_b32 s56, vcc_lo, s22
	v_lshl_add_u64 v[188:189], s[52:53], 0, v[180:181]
	s_add_i32 m0, s41, 0xc000
	ds_read_b128 v[146:149], v212
	ds_read_b128 v[150:153], v212 offset:1024
	ds_read_b128 v[154:157], v212 offset:2048
	ds_read_b128 v[158:161], v212 offset:3072
	ds_read_b128 v[162:165], v212 offset:4096
	ds_read_b128 v[166:169], v212 offset:5120
	ds_read_b128 v[170:173], v212 offset:6144
	ds_read_b128 v[184:187], v212 offset:7168
	global_load_lds_dwordx4 v[188:189], off
	v_lshl_add_u64 v[188:189], s[52:53], 0, v[182:183]
	s_add_i32 m0, s41, 0xe000
	s_nop 0
	global_load_lds_dwordx4 v[188:189], off
	s_waitcnt lgkmcnt(8)
	s_barrier
	s_waitcnt lgkmcnt(0)


	v_mfma_f32_16x16x32_bf16 v[142:145], v[102:105], v[146:149], v[142:145]
	v_mfma_f32_16x16x32_bf16 v[138:141], v[114:117], v[146:149], v[138:141]
	v_mfma_f32_16x16x32_bf16 v[134:137], v[102:105], v[154:157], v[134:137]
	v_mfma_f32_16x16x32_bf16 v[118:121], v[114:117], v[154:157], v[118:121]
	v_mfma_f32_16x16x32_bf16 v[110:113], v[102:105], v[162:165], v[110:113]
	v_mfma_f32_16x16x32_bf16 v[90:93], v[114:117], v[162:165], v[90:93]
	v_mfma_f32_16x16x32_bf16 v[82:85], v[102:105], v[170:173], v[82:85]
	v_mfma_f32_16x16x32_bf16 v[78:81], v[114:117], v[170:173], v[78:81]
	v_mfma_f32_16x16x32_bf16 v[142:145], v[106:109], v[150:153], v[142:145]
	v_mfma_f32_16x16x32_bf16 v[138:141], v[122:125], v[150:153], v[138:141]
	v_mfma_f32_16x16x32_bf16 v[134:137], v[106:109], v[158:161], v[134:137]
	v_mfma_f32_16x16x32_bf16 v[118:121], v[122:125], v[158:161], v[118:121]
	v_mfma_f32_16x16x32_bf16 v[110:113], v[106:109], v[166:169], v[110:113]
	v_mfma_f32_16x16x32_bf16 v[90:93], v[122:125], v[166:169], v[90:93]
	v_mfma_f32_16x16x32_bf16 v[82:85], v[106:109], v[184:187], v[82:85]
	v_mfma_f32_16x16x32_bf16 v[78:81], v[122:125], v[184:187], v[78:81]

	s_barrier
	s_add_i32 s69, 0, 0x14000
	v_add_u32_e32 v202, s69, v210
	s_add_i32 s52, s68, s40
	ds_read_b128 v[188:191], v202
	ds_read_b128 v[214:217], v202 offset:1024
	ds_read_b128 v[218:221], v202 offset:2048
	ds_read_b128 v[222:225], v202 offset:3072
	v_lshl_add_u64 v[202:203], s[56:57], 0, v[0:1]
	s_mov_b32 m0, s52
	v_lshl_add_u64 v[204:205], s[56:57], 0, v[178:179]
	global_load_lds_dwordx4 v[202:203], off
	s_add_i32 m0, s52, 0x2000
	s_nop 0
	global_load_lds_dwordx4 v[204:205], off
	s_barrier
	s_waitcnt lgkmcnt(0)


	v_mfma_f32_16x16x32_bf16 v[130:133], v[188:191], v[146:149], v[130:133]
	v_mfma_f32_16x16x32_bf16 v[126:129], v[218:221], v[146:149], v[126:129]
	v_mfma_f32_16x16x32_bf16 v[98:101], v[188:191], v[154:157], v[98:101]
	v_mfma_f32_16x16x32_bf16 v[94:97], v[218:221], v[154:157], v[94:97]
	v_mfma_f32_16x16x32_bf16 v[86:89], v[188:191], v[162:165], v[86:89]
	v_mfma_f32_16x16x32_bf16 v[74:77], v[218:221], v[162:165], v[74:77]
	v_mfma_f32_16x16x32_bf16 v[70:73], v[188:191], v[170:173], v[70:73]
	v_mfma_f32_16x16x32_bf16 v[66:69], v[218:221], v[170:173], v[66:69]
	v_mfma_f32_16x16x32_bf16 v[130:133], v[214:217], v[150:153], v[130:133]
	v_mfma_f32_16x16x32_bf16 v[126:129], v[222:225], v[150:153], v[126:129]
	v_mfma_f32_16x16x32_bf16 v[98:101], v[214:217], v[158:161], v[98:101]
	v_mfma_f32_16x16x32_bf16 v[94:97], v[222:225], v[158:161], v[94:97]
	v_mfma_f32_16x16x32_bf16 v[86:89], v[214:217], v[166:169], v[86:89]
	v_mfma_f32_16x16x32_bf16 v[74:77], v[222:225], v[166:169], v[74:77]
	v_mfma_f32_16x16x32_bf16 v[70:73], v[214:217], v[184:187], v[70:73]
	v_mfma_f32_16x16x32_bf16 v[66:69], v[222:225], v[184:187], v[66:69]

	s_mov_b32 m0, s41
	v_lshl_add_u64 v[226:227], s[58:59], 0, v[0:1]
	s_barrier
	ds_read_b128 v[146:149], v212 offset:16384
	ds_read_b128 v[150:153], v212 offset:17408
	ds_read_b128 v[154:157], v212 offset:18432
	ds_read_b128 v[158:161], v212 offset:19456
	ds_read_b128 v[162:165], v212 offset:20480
	ds_read_b128 v[166:169], v212 offset:21504
	ds_read_b128 v[170:173], v212 offset:22528
	ds_read_b128 v[184:187], v212 offset:23552
	global_load_lds_dwordx4 v[226:227], off
	v_lshl_add_u64 v[228:229], s[58:59], 0, v[178:179]
	s_mov_b32 m0, s42
	s_nop 0
	global_load_lds_dwordx4 v[228:229], off
	s_barrier
	s_waitcnt lgkmcnt(0)


	v_mfma_f32_16x16x32_bf16 v[62:65], v[102:105], v[146:149], v[62:65]
	v_mfma_f32_16x16x32_bf16 v[58:61], v[114:117], v[146:149], v[58:61]
	v_mfma_f32_16x16x32_bf16 v[54:57], v[102:105], v[154:157], v[54:57]
	v_mfma_f32_16x16x32_bf16 v[42:45], v[114:117], v[154:157], v[42:45]
	v_mfma_f32_16x16x32_bf16 v[38:41], v[102:105], v[162:165], v[38:41]
	v_mfma_f32_16x16x32_bf16 v[26:29], v[114:117], v[162:165], v[26:29]
	v_mfma_f32_16x16x32_bf16 v[14:17], v[102:105], v[170:173], v[14:17]
	v_mfma_f32_16x16x32_bf16 v[10:13], v[114:117], v[170:173], v[10:13]
	v_mfma_f32_16x16x32_bf16 v[62:65], v[106:109], v[150:153], v[62:65]
	v_mfma_f32_16x16x32_bf16 v[58:61], v[122:125], v[150:153], v[58:61]
	v_mfma_f32_16x16x32_bf16 v[54:57], v[106:109], v[158:161], v[54:57]
	v_mfma_f32_16x16x32_bf16 v[42:45], v[122:125], v[158:161], v[42:45]
	v_mfma_f32_16x16x32_bf16 v[38:41], v[106:109], v[166:169], v[38:41]
	v_mfma_f32_16x16x32_bf16 v[26:29], v[122:125], v[166:169], v[26:29]
	v_mfma_f32_16x16x32_bf16 v[14:17], v[106:109], v[184:187], v[14:17]
	v_mfma_f32_16x16x32_bf16 v[10:13], v[122:125], v[184:187], v[10:13]

	s_barrier
	s_add_u32 s52, s56, 0x40000
	s_addc_u32 s53, s57, 0
	s_add_i32 s68, s69, s40
	v_lshl_add_u64 v[102:103], s[52:53], 0, v[0:1]
	s_mov_b32 m0, s68
	s_nop 0
	global_load_lds_dwordx4 v[102:103], off
	v_lshl_add_u64 v[102:103], s[52:53], 0, v[178:179]
	s_add_i32 m0, s68, 0x2000
	s_nop 0
	global_load_lds_dwordx4 v[102:103], off
	s_waitcnt vmcnt(6)
	s_barrier

	v_mfma_f32_16x16x32_bf16 v[50:53], v[188:191], v[146:149], v[50:53]
	v_mfma_f32_16x16x32_bf16 v[46:49], v[218:221], v[146:149], v[46:49]
	v_mfma_f32_16x16x32_bf16 v[34:37], v[188:191], v[154:157], v[34:37]
	v_mfma_f32_16x16x32_bf16 v[30:33], v[218:221], v[154:157], v[30:33]
	v_mfma_f32_16x16x32_bf16 v[22:25], v[188:191], v[162:165], v[22:25]
	v_mfma_f32_16x16x32_bf16 v[18:21], v[218:221], v[162:165], v[18:21]
	v_mfma_f32_16x16x32_bf16 v[6:9], v[188:191], v[170:173], v[6:9]
	v_mfma_f32_16x16x32_bf16 v[2:5], v[218:221], v[170:173], v[2:5]
	v_mfma_f32_16x16x32_bf16 v[50:53], v[214:217], v[150:153], v[50:53]
	v_mfma_f32_16x16x32_bf16 v[46:49], v[222:225], v[150:153], v[46:49]
	v_mfma_f32_16x16x32_bf16 v[34:37], v[214:217], v[158:161], v[34:37]
	v_mfma_f32_16x16x32_bf16 v[30:33], v[222:225], v[158:161], v[30:33]
	v_mfma_f32_16x16x32_bf16 v[22:25], v[214:217], v[166:169], v[22:25]
	v_mfma_f32_16x16x32_bf16 v[18:21], v[222:225], v[166:169], v[18:21]
	v_mfma_f32_16x16x32_bf16 v[6:9], v[214:217], v[184:187], v[6:9]
	v_mfma_f32_16x16x32_bf16 v[2:5], v[222:225], v[184:187], v[2:5]

	s_add_i32 s68, 0, 0x18000
	v_add_u32_e32 v122, s68, v210
	s_barrier
	ds_read_b128 v[102:105], v122
	ds_read_b128 v[106:109], v122 offset:1024
	ds_read_b128 v[114:117], v122 offset:2048
	ds_read_b128 v[122:125], v122 offset:3072
	s_add_u32 s52, s58, 0x40000
	s_addc_u32 s53, s59, 0
	s_mov_b32 m0, s43
	v_lshl_add_u64 v[188:189], s[52:53], 0, v[0:1]
	ds_read_b128 v[146:149], v212 offset:32768
	ds_read_b128 v[150:153], v212 offset:33792
	ds_read_b128 v[154:157], v212 offset:34816
	ds_read_b128 v[158:161], v212 offset:35840
	ds_read_b128 v[162:165], v212 offset:36864
	ds_read_b128 v[166:169], v212 offset:37888
	ds_read_b128 v[170:173], v212 offset:38912
	ds_read_b128 v[184:187], v212 offset:39936
	global_load_lds_dwordx4 v[188:189], off
	v_lshl_add_u64 v[188:189], s[52:53], 0, v[178:179]
	s_mov_b32 m0, s62
	s_nop 0
	global_load_lds_dwordx4 v[188:189], off
	s_waitcnt lgkmcnt(8)
	s_barrier
	s_waitcnt lgkmcnt(0)


	v_mfma_f32_16x16x32_bf16 v[142:145], v[102:105], v[146:149], v[142:145]
	v_mfma_f32_16x16x32_bf16 v[138:141], v[114:117], v[146:149], v[138:141]
	v_mfma_f32_16x16x32_bf16 v[134:137], v[102:105], v[154:157], v[134:137]
	v_mfma_f32_16x16x32_bf16 v[118:121], v[114:117], v[154:157], v[118:121]
	v_mfma_f32_16x16x32_bf16 v[110:113], v[102:105], v[162:165], v[110:113]
	v_mfma_f32_16x16x32_bf16 v[90:93], v[114:117], v[162:165], v[90:93]
	v_mfma_f32_16x16x32_bf16 v[82:85], v[102:105], v[170:173], v[82:85]
	v_mfma_f32_16x16x32_bf16 v[78:81], v[114:117], v[170:173], v[78:81]
	v_mfma_f32_16x16x32_bf16 v[142:145], v[106:109], v[150:153], v[142:145]
	v_mfma_f32_16x16x32_bf16 v[138:141], v[122:125], v[150:153], v[138:141]
	v_mfma_f32_16x16x32_bf16 v[134:137], v[106:109], v[158:161], v[134:137]
	v_mfma_f32_16x16x32_bf16 v[118:121], v[122:125], v[158:161], v[118:121]
	v_mfma_f32_16x16x32_bf16 v[110:113], v[106:109], v[166:169], v[110:113]
	v_mfma_f32_16x16x32_bf16 v[90:93], v[122:125], v[166:169], v[90:93]
	v_mfma_f32_16x16x32_bf16 v[82:85], v[106:109], v[184:187], v[82:85]
	v_mfma_f32_16x16x32_bf16 v[78:81], v[122:125], v[184:187], v[78:81]

	s_barrier
	s_add_i32 s58, 0, 0x1c000
	s_add_i32 s52, s68, s40
	v_add_u32_e32 v213, s58, v210
	v_lshl_add_u64 v[202:203], v[202:203], 0, s[60:61]
	s_mov_b32 m0, s52
	ds_read_b128 v[188:191], v213
	ds_read_b128 v[214:217], v213 offset:1024
	ds_read_b128 v[218:221], v213 offset:2048
	ds_read_b128 v[222:225], v213 offset:3072
	global_load_lds_dwordx4 v[202:203], off
	v_lshl_add_u64 v[202:203], v[204:205], 0, s[60:61]
	s_add_i32 m0, s52, 0x2000
	s_nop 0
	global_load_lds_dwordx4 v[202:203], off
	s_barrier
	s_waitcnt lgkmcnt(0)


	v_mfma_f32_16x16x32_bf16 v[130:133], v[188:191], v[146:149], v[130:133]
	v_mfma_f32_16x16x32_bf16 v[126:129], v[218:221], v[146:149], v[126:129]
	v_mfma_f32_16x16x32_bf16 v[98:101], v[188:191], v[154:157], v[98:101]
	v_mfma_f32_16x16x32_bf16 v[94:97], v[218:221], v[154:157], v[94:97]
	v_mfma_f32_16x16x32_bf16 v[86:89], v[188:191], v[162:165], v[86:89]
	v_mfma_f32_16x16x32_bf16 v[74:77], v[218:221], v[162:165], v[74:77]
	v_mfma_f32_16x16x32_bf16 v[70:73], v[188:191], v[170:173], v[70:73]
	v_mfma_f32_16x16x32_bf16 v[66:69], v[218:221], v[170:173], v[66:69]
	v_mfma_f32_16x16x32_bf16 v[130:133], v[214:217], v[150:153], v[130:133]
	v_mfma_f32_16x16x32_bf16 v[126:129], v[222:225], v[150:153], v[126:129]
	v_mfma_f32_16x16x32_bf16 v[98:101], v[214:217], v[158:161], v[98:101]
	v_mfma_f32_16x16x32_bf16 v[94:97], v[222:225], v[158:161], v[94:97]
	v_mfma_f32_16x16x32_bf16 v[86:89], v[214:217], v[166:169], v[86:89]
	v_mfma_f32_16x16x32_bf16 v[74:77], v[222:225], v[166:169], v[74:77]
	v_mfma_f32_16x16x32_bf16 v[70:73], v[214:217], v[184:187], v[70:73]
	v_mfma_f32_16x16x32_bf16 v[66:69], v[222:225], v[184:187], v[66:69]

	s_mov_b32 m0, s67
	v_lshl_add_u64 v[202:203], v[226:227], 0, s[60:61]
	s_barrier
	ds_read_b128 v[146:149], v212 offset:49152
	ds_read_b128 v[150:153], v212 offset:50176
	ds_read_b128 v[154:157], v212 offset:51200
	ds_read_b128 v[158:161], v212 offset:52224
	ds_read_b128 v[162:165], v212 offset:53248
	ds_read_b128 v[166:169], v212 offset:54272
	ds_read_b128 v[170:173], v212 offset:55296
	ds_read_b128 v[184:187], v212 offset:56320
	global_load_lds_dwordx4 v[202:203], off
	v_lshl_add_u64 v[202:203], v[228:229], 0, s[60:61]
	s_mov_b32 m0, s90
	s_nop 0
	global_load_lds_dwordx4 v[202:203], off
	s_barrier
	s_waitcnt lgkmcnt(0)


	v_mfma_f32_16x16x32_bf16 v[62:65], v[102:105], v[146:149], v[62:65]
	v_mfma_f32_16x16x32_bf16 v[58:61], v[114:117], v[146:149], v[58:61]
	v_mfma_f32_16x16x32_bf16 v[54:57], v[102:105], v[154:157], v[54:57]
	v_mfma_f32_16x16x32_bf16 v[42:45], v[114:117], v[154:157], v[42:45]
	v_mfma_f32_16x16x32_bf16 v[38:41], v[102:105], v[162:165], v[38:41]
	v_mfma_f32_16x16x32_bf16 v[26:29], v[114:117], v[162:165], v[26:29]
	v_mfma_f32_16x16x32_bf16 v[14:17], v[102:105], v[170:173], v[14:17]
	v_mfma_f32_16x16x32_bf16 v[10:13], v[114:117], v[170:173], v[10:13]
	v_mfma_f32_16x16x32_bf16 v[62:65], v[106:109], v[150:153], v[62:65]
	v_mfma_f32_16x16x32_bf16 v[58:61], v[122:125], v[150:153], v[58:61]
	v_mfma_f32_16x16x32_bf16 v[54:57], v[106:109], v[158:161], v[54:57]
	v_mfma_f32_16x16x32_bf16 v[42:45], v[122:125], v[158:161], v[42:45]
	v_mfma_f32_16x16x32_bf16 v[38:41], v[106:109], v[166:169], v[38:41]
	v_mfma_f32_16x16x32_bf16 v[26:29], v[122:125], v[166:169], v[26:29]
	v_mfma_f32_16x16x32_bf16 v[14:17], v[106:109], v[184:187], v[14:17]
	v_mfma_f32_16x16x32_bf16 v[10:13], v[122:125], v[184:187], v[10:13]

	s_barrier
	s_add_u32 s52, s56, 0x40080
	s_addc_u32 s53, s57, 0
	s_add_i32 s56, s58, s40
	v_lshl_add_u64 v[102:103], s[52:53], 0, v[0:1]
	s_mov_b32 m0, s56
	s_nop 0
	global_load_lds_dwordx4 v[102:103], off
	v_lshl_add_u64 v[102:103], s[52:53], 0, v[178:179]
	s_add_i32 m0, s56, 0x2000
	s_nop 0
	global_load_lds_dwordx4 v[102:103], off
	s_waitcnt vmcnt(6)
	s_barrier

	v_mfma_f32_16x16x32_bf16 v[50:53], v[188:191], v[146:149], v[50:53]
	v_mfma_f32_16x16x32_bf16 v[46:49], v[218:221], v[146:149], v[46:49]
	v_mfma_f32_16x16x32_bf16 v[34:37], v[188:191], v[154:157], v[34:37]
	v_mfma_f32_16x16x32_bf16 v[30:33], v[218:221], v[154:157], v[30:33]
	v_mfma_f32_16x16x32_bf16 v[22:25], v[188:191], v[162:165], v[22:25]
	v_mfma_f32_16x16x32_bf16 v[18:21], v[218:221], v[162:165], v[18:21]
	v_mfma_f32_16x16x32_bf16 v[6:9], v[188:191], v[170:173], v[6:9]
	v_mfma_f32_16x16x32_bf16 v[2:5], v[218:221], v[170:173], v[2:5]
	v_mfma_f32_16x16x32_bf16 v[50:53], v[214:217], v[150:153], v[50:53]
	v_mfma_f32_16x16x32_bf16 v[46:49], v[222:225], v[150:153], v[46:49]
	v_mfma_f32_16x16x32_bf16 v[34:37], v[214:217], v[158:161], v[34:37]
	v_mfma_f32_16x16x32_bf16 v[30:33], v[222:225], v[158:161], v[30:33]
	v_mfma_f32_16x16x32_bf16 v[22:25], v[214:217], v[166:169], v[22:25]
	v_mfma_f32_16x16x32_bf16 v[18:21], v[222:225], v[166:169], v[18:21]
	v_mfma_f32_16x16x32_bf16 v[6:9], v[214:217], v[184:187], v[6:9]
	v_mfma_f32_16x16x32_bf16 v[2:5], v[222:225], v[184:187], v[2:5]

	s_add_i32 vcc_hi, vcc_hi, 2
	s_add_u32 s22, s22, 0x100
	s_addc_u32 s23, s23, 0
	s_cmp_gt_u32 vcc_hi, 13
	s_mov_b64 s[52:53], s[54:55]
	s_barrier
	s_cbranch_scc0 .LBB0_801
	s_sub_i32 s1, s96, 32
	s_lshr_b32 s1, s1, 2
	s_add_i32 s1, s1, 1
	s_cmp_lt_i32 s96, 32
	v_lshl_or_b32 v102, s97, 8, v211
	s_cselect_b32 s1, 0, s1
	s_mul_hi_u32 s5, s1, 0x6000
	s_mulk_i32 s1, 0x6000
	v_ashrrev_i32_e32 v103, 31, v102
	v_lshl_add_u32 v146, s96, 8, v209
	s_cselect_b32 s23, s65, s94
	s_cselect_b32 s22, s66, s91
	s_add_u32 s52, s63, s1
	v_lshlrev_b64 v[184:185], 2, v[102:103]
	v_ashrrev_i32_e32 v147, 31, v146
	s_addc_u32 s53, s64, s5
	v_lshl_add_u64 v[186:187], s[22:23], 0, v[184:185]
	v_lshlrev_b64 v[188:189], 12, v[146:147]
	v_lshl_add_u64 v[102:103], s[52:53], 0, v[184:185]
	v_lshl_add_u64 v[148:149], v[186:187], 0, v[188:189]
	global_load_dwordx4 v[122:125], v[102:103], off
	global_load_dwordx4 v[114:117], v[102:103], off offset:64
	global_load_dwordx4 v[106:109], v[102:103], off offset:512
	s_nop 0
	global_load_dwordx4 v[102:105], v[102:103], off offset:576
	s_nop 0
	global_load_dwordx4 v[214:217], v[148:149], off
	global_load_dwordx4 v[218:221], v[148:149], off offset:64
	global_load_dwordx4 v[222:225], v[148:149], off offset:512
	global_load_dwordx4 v[226:229], v[148:149], off offset:576
	v_or_b32_e32 v148, 16, v146
	v_ashrrev_i32_e32 v149, 31, v148
	v_lshlrev_b64 v[202:203], 12, v[148:149]
	v_lshl_add_u64 v[148:149], v[186:187], 0, v[202:203]
	global_load_dwordx4 v[230:233], v[148:149], off
	global_load_dwordx4 v[234:237], v[148:149], off offset:64
	global_load_dwordx4 v[238:241], v[148:149], off offset:512
	global_load_dwordx4 v[242:245], v[148:149], off offset:576
	v_or_b32_e32 v148, 32, v146
	v_ashrrev_i32_e32 v149, 31, v148
	v_lshlrev_b64 v[204:205], 12, v[148:149]
	v_lshl_add_u64 v[148:149], v[186:187], 0, v[204:205]
	v_or_b32_e32 v146, 48, v146
	global_load_dwordx4 v[246:249], v[148:149], off
	global_load_dwordx4 v[170:173], v[148:149], off offset:64
	global_load_dwordx4 v[166:169], v[148:149], off offset:512
	global_load_dwordx4 v[162:165], v[148:149], off offset:576
	v_ashrrev_i32_e32 v147, 31, v146
	v_lshlrev_b64 v[190:191], 12, v[146:147]
	v_lshl_add_u64 v[146:147], v[186:187], 0, v[190:191]
	global_load_dwordx4 v[158:161], v[146:147], off
	global_load_dwordx4 v[154:157], v[146:147], off offset:64
	global_load_dwordx4 v[150:153], v[146:147], off offset:512
	s_nop 0
	global_load_dwordx4 v[146:149], v[146:147], off offset:576
	s_mov_b64 s[22:23], 0x80000
	s_and_b64 vcc, exec, s[2:3]
	s_mov_b32 s97, s0
	s_mov_b32 s96, s4
	s_mov_b64 s[54:55], s[18:19]
	s_mov_b64 s[52:53], s[6:7]
	s_waitcnt vmcnt(0)
	v_pk_fma_f32 v[142:143], v[142:143], v[122:123], v[214:215]
	v_lshl_add_u64 v[214:215], s[26:27], 0, v[188:189]
	v_lshl_add_u64 v[214:215], v[214:215], 0, v[184:185]
	v_pk_fma_f32 v[132:133], v[132:133], v[108:109], v[224:225]
	v_pk_fma_f32 v[130:131], v[130:131], v[106:107], v[222:223]
	global_store_dwordx4 v[214:215], v[130:133], off offset:512
	v_pk_fma_f32 v[128:129], v[128:129], v[104:105], v[228:229]
	v_pk_fma_f32 v[100:101], v[100:101], v[108:109], v[240:241]
	v_lshl_add_u64 v[130:131], s[26:27], 0, v[202:203]
	v_lshl_add_u64 v[130:131], v[130:131], 0, v[184:185]
	v_pk_fma_f32 v[98:99], v[98:99], v[106:107], v[238:239]
	global_store_dwordx4 v[130:131], v[98:101], off offset:512
	v_pk_fma_f32 v[126:127], v[126:127], v[102:103], v[226:227]
	v_pk_fma_f32 v[96:97], v[96:97], v[104:105], v[244:245]
	v_lshl_add_u64 v[98:99], s[26:27], 0, v[204:205]
	v_lshl_add_u64 v[98:99], v[98:99], 0, v[184:185]
	v_pk_fma_f32 v[76:77], v[76:77], v[104:105], v[164:165]
	v_pk_fma_f32 v[74:75], v[74:75], v[102:103], v[162:163]
	global_store_dwordx4 v[98:99], v[74:77], off offset:576
	v_pk_fma_f32 v[94:95], v[94:95], v[102:103], v[242:243]
	v_pk_fma_f32 v[144:145], v[144:145], v[124:125], v[216:217]
	v_pk_fma_f32 v[74:75], v[82:83], v[122:123], v[158:159]
	v_lshl_add_u64 v[82:83], s[26:27], 0, v[190:191]
	v_pk_fma_f32 v[76:77], v[84:85], v[124:125], v[160:161]
	v_lshl_add_u64 v[82:83], v[82:83], 0, v[184:185]
	v_pk_fma_f32 v[140:141], v[140:141], v[116:117], v[220:221]
	v_pk_fma_f32 v[138:139], v[138:139], v[114:115], v[218:219]
	global_store_dwordx4 v[214:215], v[126:129], off offset:576
	v_pk_fma_f32 v[120:121], v[120:121], v[116:117], v[236:237]
	v_pk_fma_f32 v[118:119], v[118:119], v[114:115], v[234:235]
	v_pk_fma_f32 v[128:129], v[136:137], v[124:125], v[232:233]
	v_pk_fma_f32 v[126:127], v[134:135], v[122:123], v[230:231]
	global_store_dwordx4 v[130:131], v[94:97], off offset:576
	v_pk_fma_f32 v[92:93], v[92:93], v[116:117], v[172:173]
	v_pk_fma_f32 v[90:91], v[90:91], v[114:115], v[170:171]
	v_pk_fma_f32 v[96:97], v[112:113], v[124:125], v[248:249]
	v_pk_fma_f32 v[94:95], v[110:111], v[122:123], v[246:247]
	v_pk_fma_f32 v[88:89], v[88:89], v[108:109], v[168:169]
	v_pk_fma_f32 v[86:87], v[86:87], v[106:107], v[166:167]
	global_store_dwordx4 v[82:83], v[74:77], off
	v_pk_fma_f32 v[72:73], v[72:73], v[108:109], v[152:153]
	v_pk_fma_f32 v[70:71], v[70:71], v[106:107], v[150:151]
	v_pk_fma_f32 v[76:77], v[80:81], v[116:117], v[156:157]
	v_pk_fma_f32 v[74:75], v[78:79], v[114:115], v[154:155]
	v_pk_fma_f32 v[68:69], v[68:69], v[104:105], v[148:149]
	v_pk_fma_f32 v[66:67], v[66:67], v[102:103], v[146:147]
	v_lshl_add_u64 v[100:101], v[188:189], 0, s[22:23]
	global_store_dwordx4 v[214:215], v[142:145], off
	global_store_dwordx4 v[214:215], v[138:141], off offset:64
	global_store_dwordx4 v[130:131], v[126:129], off
	global_store_dwordx4 v[130:131], v[118:121], off offset:64
	global_store_dwordx4 v[98:99], v[94:97], off
	global_store_dwordx4 v[98:99], v[90:93], off offset:64
	global_store_dwordx4 v[98:99], v[86:89], off offset:512
	global_store_dwordx4 v[82:83], v[74:77], off offset:64
	global_store_dwordx4 v[82:83], v[70:73], off offset:512
	global_store_dwordx4 v[82:83], v[66:69], off offset:576
	s_mov_b64 s[22:23], 0x90000
	v_lshl_add_u64 v[150:151], v[188:189], 0, s[22:23]
	v_lshl_add_u64 v[66:67], v[186:187], 0, v[100:101]
	global_load_dwordx4 v[96:99], v[66:67], off
	global_load_dwordx4 v[110:113], v[66:67], off offset:64
	global_load_dwordx4 v[118:121], v[66:67], off offset:512
	global_load_dwordx4 v[126:129], v[66:67], off offset:576
	s_mov_b64 s[22:23], 0xa0000
	v_lshl_add_u64 v[66:67], v[186:187], 0, v[150:151]
	v_lshl_add_u64 v[152:153], v[188:189], 0, s[22:23]
	global_load_dwordx4 v[130:133], v[66:67], off
	global_load_dwordx4 v[134:137], v[66:67], off offset:64
	global_load_dwordx4 v[138:141], v[66:67], off offset:512
	global_load_dwordx4 v[142:145], v[66:67], off offset:576
	v_lshl_add_u64 v[66:67], v[186:187], 0, v[152:153]
	s_mov_b64 s[22:23], 0xb0000
	global_load_dwordx4 v[146:149], v[66:67], off
	global_load_dwordx4 v[90:93], v[66:67], off offset:64
	global_load_dwordx4 v[86:89], v[66:67], off offset:512
	global_load_dwordx4 v[82:85], v[66:67], off offset:576
	v_lshl_add_u64 v[94:95], v[188:189], 0, s[22:23]
	v_lshl_add_u64 v[66:67], v[186:187], 0, v[94:95]
	global_load_dwordx4 v[78:81], v[66:67], off
	global_load_dwordx4 v[74:77], v[66:67], off offset:64
	global_load_dwordx4 v[70:73], v[66:67], off offset:512
	s_nop 0
	global_load_dwordx4 v[66:69], v[66:67], off offset:576
	s_waitcnt vmcnt(0)
	v_pk_fma_f32 v[62:63], v[62:63], v[122:123], v[96:97]
	v_lshl_add_u64 v[96:97], s[26:27], 0, v[100:101]
	v_lshl_add_u64 v[96:97], v[96:97], 0, v[184:185]
	v_pk_fma_f32 v[52:53], v[52:53], v[108:109], v[120:121]
	v_pk_fma_f32 v[50:51], v[50:51], v[106:107], v[118:119]
	global_store_dwordx4 v[96:97], v[50:53], off offset:512
	v_pk_fma_f32 v[36:37], v[36:37], v[108:109], v[140:141]
	v_pk_fma_f32 v[34:35], v[34:35], v[106:107], v[138:139]
	v_lshl_add_u64 v[50:51], s[26:27], 0, v[150:151]
	v_lshl_add_u64 v[50:51], v[50:51], 0, v[184:185]
	global_store_dwordx4 v[50:51], v[34:37], off offset:512
	v_pk_fma_f32 v[20:21], v[20:21], v[104:105], v[84:85]
	v_pk_fma_f32 v[18:19], v[18:19], v[102:103], v[82:83]
	v_lshl_add_u64 v[34:35], s[26:27], 0, v[152:153]
	v_lshl_add_u64 v[34:35], v[34:35], 0, v[184:185]
	v_pk_fma_f32 v[48:49], v[48:49], v[104:105], v[128:129]
	v_pk_fma_f32 v[46:47], v[46:47], v[102:103], v[126:127]
	v_pk_fma_f32 v[32:33], v[32:33], v[104:105], v[144:145]
	v_pk_fma_f32 v[30:31], v[30:31], v[102:103], v[142:143]
	global_store_dwordx4 v[34:35], v[18:21], off offset:576
	v_pk_fma_f32 v[64:65], v[64:65], v[124:125], v[98:99]
	v_pk_fma_f32 v[60:61], v[60:61], v[116:117], v[112:113]
	v_lshl_add_u64 v[18:19], s[26:27], 0, v[94:95]
	v_pk_fma_f32 v[58:59], v[58:59], v[114:115], v[110:111]
	global_store_dwordx4 v[96:97], v[46:49], off offset:576
	v_pk_fma_f32 v[44:45], v[44:45], v[116:117], v[136:137]
	v_pk_fma_f32 v[42:43], v[42:43], v[114:115], v[134:135]
	v_pk_fma_f32 v[48:49], v[56:57], v[124:125], v[132:133]
	v_pk_fma_f32 v[46:47], v[54:55], v[122:123], v[130:131]
	global_store_dwordx4 v[50:51], v[30:33], off offset:576
	v_pk_fma_f32 v[28:29], v[28:29], v[116:117], v[92:93]
	v_pk_fma_f32 v[26:27], v[26:27], v[114:115], v[90:91]
	v_pk_fma_f32 v[32:33], v[40:41], v[124:125], v[148:149]
	v_pk_fma_f32 v[30:31], v[38:39], v[122:123], v[146:147]
	v_pk_fma_f32 v[24:25], v[24:25], v[108:109], v[88:89]
	v_pk_fma_f32 v[22:23], v[22:23], v[106:107], v[86:87]
	v_pk_fma_f32 v[16:17], v[16:17], v[124:125], v[80:81]
	v_pk_fma_f32 v[14:15], v[14:15], v[122:123], v[78:79]
	v_lshl_add_u64 v[18:19], v[18:19], 0, v[184:185]
	v_pk_fma_f32 v[12:13], v[12:13], v[116:117], v[76:77]
	v_pk_fma_f32 v[10:11], v[10:11], v[114:115], v[74:75]
	v_pk_fma_f32 v[8:9], v[8:9], v[108:109], v[72:73]
	v_pk_fma_f32 v[6:7], v[6:7], v[106:107], v[70:71]
	v_pk_fma_f32 v[4:5], v[4:5], v[104:105], v[68:69]
	v_pk_fma_f32 v[2:3], v[2:3], v[102:103], v[66:67]
	global_store_dwordx4 v[96:97], v[62:65], off
	global_store_dwordx4 v[96:97], v[58:61], off offset:64
	global_store_dwordx4 v[50:51], v[46:49], off
	global_store_dwordx4 v[50:51], v[42:45], off offset:64
	global_store_dwordx4 v[34:35], v[30:33], off
	global_store_dwordx4 v[34:35], v[26:29], off offset:64
	global_store_dwordx4 v[34:35], v[22:25], off offset:512
	global_store_dwordx4 v[18:19], v[14:17], off
	global_store_dwordx4 v[18:19], v[10:13], off offset:64
	global_store_dwordx4 v[18:19], v[6:9], off offset:512
	global_store_dwordx4 v[18:19], v[2:5], off offset:576
	s_cbranch_vccz .LBB0_798
	s_waitcnt vmcnt(0)
	v_readlane_b32 s66, v252, 44
	v_readlane_b32 s96, v254, 60
	v_readlane_b32 s64, v254, 62
	v_readlane_b32 s90, v255, 0
	s_cmpk_gt_u32 s70, 0xff
	v_readlane_b32 s67, v252, 45
	v_readlane_b32 s97, v254, 61
	v_readlane_b32 s65, v254, 63
	v_readlane_b32 s91, v255, 1
	s_cbranch_scc1 .LBB0_805
	s_barrier

.LBB0_960:
	s_add_u32 s54, s52, 0xfffc0080
	s_addc_u32 s55, s53, -1
	s_add_i32 s68, 0, 0x10000
	v_add_u32_e32 v136, s68, v139
	ds_read_b128 v[142:145], v136
	ds_read_b128 v[146:149], v136 offset:1024
	ds_read_b128 v[150:153], v136 offset:2048
	ds_read_b128 v[154:157], v136 offset:3072
	s_cmp_eq_u32 s23, 12
	s_cselect_b32 s57, s5, s55
	s_cselect_b32 s56, s66, s54
	s_cselect_b32 s55, s1, s22
	s_cselect_b32 s54, s67, s90
	v_lshl_add_u64 v[136:137], s[52:53], 0, v[132:133]
	s_add_i32 m0, s41, 0xc000
	ds_read_b128 v[158:161], v141
	ds_read_b128 v[162:165], v141 offset:1024
	ds_read_b128 v[166:169], v141 offset:2048
	ds_read_b128 v[170:173], v141 offset:3072
	ds_read_b128 v[178:181], v141 offset:4096
	ds_read_b128 v[182:185], v141 offset:5120
	ds_read_b128 v[186:189], v141 offset:6144
	ds_read_b128 v[210:213], v141 offset:7168
	global_load_lds_dwordx4 v[136:137], off
	v_lshl_add_u64 v[136:137], s[52:53], 0, v[134:135]
	s_add_i32 m0, s41, 0xe000
	s_nop 0
	global_load_lds_dwordx4 v[136:137], off
	s_waitcnt lgkmcnt(8)
	s_barrier
	s_waitcnt lgkmcnt(0)


	v_mfma_f32_16x16x32_bf16 v[126:129], v[142:145], v[158:161], v[126:129]
	v_mfma_f32_16x16x32_bf16 v[122:125], v[150:153], v[158:161], v[122:125]
	v_mfma_f32_16x16x32_bf16 v[110:113], v[142:145], v[166:169], v[110:113]
	v_mfma_f32_16x16x32_bf16 v[106:109], v[150:153], v[166:169], v[106:109]
	v_mfma_f32_16x16x32_bf16 v[94:97], v[142:145], v[178:181], v[94:97]
	v_mfma_f32_16x16x32_bf16 v[90:93], v[150:153], v[178:181], v[90:93]
	v_mfma_f32_16x16x32_bf16 v[78:81], v[142:145], v[186:189], v[78:81]
	v_mfma_f32_16x16x32_bf16 v[74:77], v[150:153], v[186:189], v[74:77]
	v_mfma_f32_16x16x32_bf16 v[126:129], v[146:149], v[162:165], v[126:129]
	v_mfma_f32_16x16x32_bf16 v[122:125], v[154:157], v[162:165], v[122:125]
	v_mfma_f32_16x16x32_bf16 v[110:113], v[146:149], v[170:173], v[110:113]
	v_mfma_f32_16x16x32_bf16 v[106:109], v[154:157], v[170:173], v[106:109]
	v_mfma_f32_16x16x32_bf16 v[94:97], v[146:149], v[182:185], v[94:97]
	v_mfma_f32_16x16x32_bf16 v[90:93], v[154:157], v[182:185], v[90:93]
	v_mfma_f32_16x16x32_bf16 v[78:81], v[146:149], v[210:213], v[78:81]
	v_mfma_f32_16x16x32_bf16 v[74:77], v[154:157], v[210:213], v[74:77]

	s_barrier
	s_add_i32 s70, 0, 0x14000
	v_add_u32_e32 v136, s70, v139
	s_add_i32 s68, s68, s40
	ds_read_b128 v[214:217], v136
	ds_read_b128 v[218:221], v136 offset:1024
	ds_read_b128 v[222:225], v136 offset:2048
	ds_read_b128 v[226:229], v136 offset:3072
	v_lshl_add_u64 v[136:137], s[54:55], 0, v[0:1]
	s_mov_b32 m0, s68
	v_lshl_add_u64 v[190:191], s[54:55], 0, v[130:131]
	global_load_lds_dwordx4 v[136:137], off
	s_add_i32 m0, s68, 0x2000
	s_nop 0
	global_load_lds_dwordx4 v[190:191], off
	s_barrier
	s_waitcnt lgkmcnt(0)


	v_mfma_f32_16x16x32_bf16 v[118:121], v[214:217], v[158:161], v[118:121]
	v_mfma_f32_16x16x32_bf16 v[114:117], v[222:225], v[158:161], v[114:117]
	v_mfma_f32_16x16x32_bf16 v[102:105], v[214:217], v[166:169], v[102:105]
	v_mfma_f32_16x16x32_bf16 v[98:101], v[222:225], v[166:169], v[98:101]
	v_mfma_f32_16x16x32_bf16 v[86:89], v[214:217], v[178:181], v[86:89]
	v_mfma_f32_16x16x32_bf16 v[82:85], v[222:225], v[178:181], v[82:85]
	v_mfma_f32_16x16x32_bf16 v[70:73], v[214:217], v[186:189], v[70:73]
	v_mfma_f32_16x16x32_bf16 v[66:69], v[222:225], v[186:189], v[66:69]
	v_mfma_f32_16x16x32_bf16 v[118:121], v[218:221], v[162:165], v[118:121]
	v_mfma_f32_16x16x32_bf16 v[114:117], v[226:229], v[162:165], v[114:117]
	v_mfma_f32_16x16x32_bf16 v[102:105], v[218:221], v[170:173], v[102:105]
	v_mfma_f32_16x16x32_bf16 v[98:101], v[226:229], v[170:173], v[98:101]
	v_mfma_f32_16x16x32_bf16 v[86:89], v[218:221], v[182:185], v[86:89]
	v_mfma_f32_16x16x32_bf16 v[82:85], v[226:229], v[182:185], v[82:85]
	v_mfma_f32_16x16x32_bf16 v[70:73], v[218:221], v[210:213], v[70:73]
	v_mfma_f32_16x16x32_bf16 v[66:69], v[226:229], v[210:213], v[66:69]

	s_mov_b32 m0, s41
	v_lshl_add_u64 v[202:203], s[56:57], 0, v[0:1]
	s_barrier
	ds_read_b128 v[158:161], v141 offset:16384
	ds_read_b128 v[162:165], v141 offset:17408
	ds_read_b128 v[166:169], v141 offset:18432
	ds_read_b128 v[170:173], v141 offset:19456
	ds_read_b128 v[178:181], v141 offset:20480
	ds_read_b128 v[182:185], v141 offset:21504
	ds_read_b128 v[186:189], v141 offset:22528
	ds_read_b128 v[210:213], v141 offset:23552
	global_load_lds_dwordx4 v[202:203], off
	v_lshl_add_u64 v[204:205], s[56:57], 0, v[130:131]
	s_mov_b32 m0, s42
	s_nop 0
	global_load_lds_dwordx4 v[204:205], off
	s_barrier
	s_waitcnt lgkmcnt(0)


	v_mfma_f32_16x16x32_bf16 v[62:65], v[142:145], v[158:161], v[62:65]
	v_mfma_f32_16x16x32_bf16 v[58:61], v[150:153], v[158:161], v[58:61]
	v_mfma_f32_16x16x32_bf16 v[46:49], v[142:145], v[166:169], v[46:49]
	v_mfma_f32_16x16x32_bf16 v[42:45], v[150:153], v[166:169], v[42:45]
	v_mfma_f32_16x16x32_bf16 v[30:33], v[142:145], v[178:181], v[30:33]
	v_mfma_f32_16x16x32_bf16 v[26:29], v[150:153], v[178:181], v[26:29]
	v_mfma_f32_16x16x32_bf16 v[14:17], v[142:145], v[186:189], v[14:17]
	v_mfma_f32_16x16x32_bf16 v[10:13], v[150:153], v[186:189], v[10:13]
	v_mfma_f32_16x16x32_bf16 v[62:65], v[146:149], v[162:165], v[62:65]
	v_mfma_f32_16x16x32_bf16 v[58:61], v[154:157], v[162:165], v[58:61]
	v_mfma_f32_16x16x32_bf16 v[46:49], v[146:149], v[170:173], v[46:49]
	v_mfma_f32_16x16x32_bf16 v[42:45], v[154:157], v[170:173], v[42:45]
	v_mfma_f32_16x16x32_bf16 v[30:33], v[146:149], v[182:185], v[30:33]
	v_mfma_f32_16x16x32_bf16 v[26:29], v[154:157], v[182:185], v[26:29]
	v_mfma_f32_16x16x32_bf16 v[14:17], v[146:149], v[210:213], v[14:17]
	v_mfma_f32_16x16x32_bf16 v[10:13], v[154:157], v[210:213], v[10:13]

	s_barrier
	s_add_u32 s68, s54, 0x40000
	s_addc_u32 s69, s55, 0
	s_add_i32 s70, s70, s40
	v_lshl_add_u64 v[142:143], s[68:69], 0, v[0:1]
	s_mov_b32 m0, s70
	s_nop 0
	global_load_lds_dwordx4 v[142:143], off
	v_lshl_add_u64 v[142:143], s[68:69], 0, v[130:131]
	s_add_i32 m0, s70, 0x2000
	s_nop 0
	global_load_lds_dwordx4 v[142:143], off
	s_waitcnt vmcnt(6)
	s_barrier

	v_mfma_f32_16x16x32_bf16 v[54:57], v[214:217], v[158:161], v[54:57]
	v_mfma_f32_16x16x32_bf16 v[50:53], v[222:225], v[158:161], v[50:53]
	v_mfma_f32_16x16x32_bf16 v[38:41], v[214:217], v[166:169], v[38:41]
	v_mfma_f32_16x16x32_bf16 v[34:37], v[222:225], v[166:169], v[34:37]
	v_mfma_f32_16x16x32_bf16 v[22:25], v[214:217], v[178:181], v[22:25]
	v_mfma_f32_16x16x32_bf16 v[18:21], v[222:225], v[178:181], v[18:21]
	v_mfma_f32_16x16x32_bf16 v[6:9], v[214:217], v[186:189], v[6:9]
	v_mfma_f32_16x16x32_bf16 v[2:5], v[222:225], v[186:189], v[2:5]
	v_mfma_f32_16x16x32_bf16 v[54:57], v[218:221], v[162:165], v[54:57]
	v_mfma_f32_16x16x32_bf16 v[50:53], v[226:229], v[162:165], v[50:53]
	v_mfma_f32_16x16x32_bf16 v[38:41], v[218:221], v[170:173], v[38:41]
	v_mfma_f32_16x16x32_bf16 v[34:37], v[226:229], v[170:173], v[34:37]
	v_mfma_f32_16x16x32_bf16 v[22:25], v[218:221], v[182:185], v[22:25]
	v_mfma_f32_16x16x32_bf16 v[18:21], v[226:229], v[182:185], v[18:21]
	v_mfma_f32_16x16x32_bf16 v[6:9], v[218:221], v[210:213], v[6:9]
	v_mfma_f32_16x16x32_bf16 v[2:5], v[226:229], v[210:213], v[2:5]

	s_add_i32 s68, 0, 0x18000
	v_add_u32_e32 v154, s68, v139
	s_barrier
	ds_read_b128 v[142:145], v154
	ds_read_b128 v[146:149], v154 offset:1024
	ds_read_b128 v[150:153], v154 offset:2048
	ds_read_b128 v[154:157], v154 offset:3072
	s_add_u32 s56, s56, 0x40000
	s_addc_u32 s57, s57, 0
	s_mov_b32 m0, s43
	v_lshl_add_u64 v[214:215], s[56:57], 0, v[0:1]
	ds_read_b128 v[158:161], v141 offset:32768
	ds_read_b128 v[162:165], v141 offset:33792
	ds_read_b128 v[166:169], v141 offset:34816
	ds_read_b128 v[170:173], v141 offset:35840
	ds_read_b128 v[178:181], v141 offset:36864
	ds_read_b128 v[182:185], v141 offset:37888
	ds_read_b128 v[186:189], v141 offset:38912
	ds_read_b128 v[210:213], v141 offset:39936
	global_load_lds_dwordx4 v[214:215], off
	v_lshl_add_u64 v[214:215], s[56:57], 0, v[130:131]
	s_mov_b32 m0, s58
	s_nop 0
	global_load_lds_dwordx4 v[214:215], off
	s_waitcnt lgkmcnt(8)
	s_barrier
	s_waitcnt lgkmcnt(0)


	v_mfma_f32_16x16x32_bf16 v[126:129], v[142:145], v[158:161], v[126:129]
	v_mfma_f32_16x16x32_bf16 v[122:125], v[150:153], v[158:161], v[122:125]
	v_mfma_f32_16x16x32_bf16 v[110:113], v[142:145], v[166:169], v[110:113]
	v_mfma_f32_16x16x32_bf16 v[106:109], v[150:153], v[166:169], v[106:109]
	v_mfma_f32_16x16x32_bf16 v[94:97], v[142:145], v[178:181], v[94:97]
	v_mfma_f32_16x16x32_bf16 v[90:93], v[150:153], v[178:181], v[90:93]
	v_mfma_f32_16x16x32_bf16 v[78:81], v[142:145], v[186:189], v[78:81]
	v_mfma_f32_16x16x32_bf16 v[74:77], v[150:153], v[186:189], v[74:77]
	v_mfma_f32_16x16x32_bf16 v[126:129], v[146:149], v[162:165], v[126:129]
	v_mfma_f32_16x16x32_bf16 v[122:125], v[154:157], v[162:165], v[122:125]
	v_mfma_f32_16x16x32_bf16 v[110:113], v[146:149], v[170:173], v[110:113]
	v_mfma_f32_16x16x32_bf16 v[106:109], v[154:157], v[170:173], v[106:109]
	v_mfma_f32_16x16x32_bf16 v[94:97], v[146:149], v[182:185], v[94:97]
	v_mfma_f32_16x16x32_bf16 v[90:93], v[154:157], v[182:185], v[90:93]
	v_mfma_f32_16x16x32_bf16 v[78:81], v[146:149], v[210:213], v[78:81]
	v_mfma_f32_16x16x32_bf16 v[74:77], v[154:157], v[210:213], v[74:77]

	s_barrier
	s_add_i32 s56, 0, 0x1c000
	s_add_i32 s57, s68, s40
	v_add_u32_e32 v209, s56, v139
	v_lshl_add_u64 v[136:137], v[136:137], 0, s[60:61]
	s_mov_b32 m0, s57
	ds_read_b128 v[214:217], v209
	ds_read_b128 v[218:221], v209 offset:1024
	ds_read_b128 v[222:225], v209 offset:2048
	ds_read_b128 v[226:229], v209 offset:3072
	global_load_lds_dwordx4 v[136:137], off
	v_lshl_add_u64 v[136:137], v[190:191], 0, s[60:61]
	s_add_i32 m0, s57, 0x2000
	s_nop 0
	global_load_lds_dwordx4 v[136:137], off
	s_barrier
	s_waitcnt lgkmcnt(0)


	v_mfma_f32_16x16x32_bf16 v[118:121], v[214:217], v[158:161], v[118:121]
	v_mfma_f32_16x16x32_bf16 v[114:117], v[222:225], v[158:161], v[114:117]
	v_mfma_f32_16x16x32_bf16 v[102:105], v[214:217], v[166:169], v[102:105]
	v_mfma_f32_16x16x32_bf16 v[98:101], v[222:225], v[166:169], v[98:101]
	v_mfma_f32_16x16x32_bf16 v[86:89], v[214:217], v[178:181], v[86:89]
	v_mfma_f32_16x16x32_bf16 v[82:85], v[222:225], v[178:181], v[82:85]
	v_mfma_f32_16x16x32_bf16 v[70:73], v[214:217], v[186:189], v[70:73]
	v_mfma_f32_16x16x32_bf16 v[66:69], v[222:225], v[186:189], v[66:69]
	v_mfma_f32_16x16x32_bf16 v[118:121], v[218:221], v[162:165], v[118:121]
	v_mfma_f32_16x16x32_bf16 v[114:117], v[226:229], v[162:165], v[114:117]
	v_mfma_f32_16x16x32_bf16 v[102:105], v[218:221], v[170:173], v[102:105]
	v_mfma_f32_16x16x32_bf16 v[98:101], v[226:229], v[170:173], v[98:101]
	v_mfma_f32_16x16x32_bf16 v[86:89], v[218:221], v[182:185], v[86:89]
	v_mfma_f32_16x16x32_bf16 v[82:85], v[226:229], v[182:185], v[82:85]
	v_mfma_f32_16x16x32_bf16 v[70:73], v[218:221], v[210:213], v[70:73]
	v_mfma_f32_16x16x32_bf16 v[66:69], v[226:229], v[210:213], v[66:69]

	s_mov_b32 m0, s59
	v_lshl_add_u64 v[136:137], v[202:203], 0, s[60:61]
	s_barrier
	ds_read_b128 v[158:161], v141 offset:49152
	ds_read_b128 v[162:165], v141 offset:50176
	ds_read_b128 v[166:169], v141 offset:51200
	ds_read_b128 v[170:173], v141 offset:52224
	ds_read_b128 v[178:181], v141 offset:53248
	ds_read_b128 v[182:185], v141 offset:54272
	ds_read_b128 v[186:189], v141 offset:55296
	ds_read_b128 v[210:213], v141 offset:56320
	global_load_lds_dwordx4 v[136:137], off
	v_lshl_add_u64 v[136:137], v[204:205], 0, s[60:61]
	s_mov_b32 m0, s62
	s_nop 0
	global_load_lds_dwordx4 v[136:137], off
	s_barrier
	s_waitcnt lgkmcnt(0)


	v_mfma_f32_16x16x32_bf16 v[62:65], v[142:145], v[158:161], v[62:65]
	v_mfma_f32_16x16x32_bf16 v[58:61], v[150:153], v[158:161], v[58:61]
	v_mfma_f32_16x16x32_bf16 v[46:49], v[142:145], v[166:169], v[46:49]
	v_mfma_f32_16x16x32_bf16 v[42:45], v[150:153], v[166:169], v[42:45]
	v_mfma_f32_16x16x32_bf16 v[30:33], v[142:145], v[178:181], v[30:33]
	v_mfma_f32_16x16x32_bf16 v[26:29], v[150:153], v[178:181], v[26:29]
	v_mfma_f32_16x16x32_bf16 v[14:17], v[142:145], v[186:189], v[14:17]
	v_mfma_f32_16x16x32_bf16 v[10:13], v[150:153], v[186:189], v[10:13]
	v_mfma_f32_16x16x32_bf16 v[62:65], v[146:149], v[162:165], v[62:65]
	v_mfma_f32_16x16x32_bf16 v[58:61], v[154:157], v[162:165], v[58:61]
	v_mfma_f32_16x16x32_bf16 v[46:49], v[146:149], v[170:173], v[46:49]
	v_mfma_f32_16x16x32_bf16 v[42:45], v[154:157], v[170:173], v[42:45]
	v_mfma_f32_16x16x32_bf16 v[30:33], v[146:149], v[182:185], v[30:33]
	v_mfma_f32_16x16x32_bf16 v[26:29], v[154:157], v[182:185], v[26:29]
	v_mfma_f32_16x16x32_bf16 v[14:17], v[146:149], v[210:213], v[14:17]
	v_mfma_f32_16x16x32_bf16 v[10:13], v[154:157], v[210:213], v[10:13]

	s_barrier
	s_add_u32 s54, s54, 0x40080
	s_addc_u32 s55, s55, 0
	s_add_i32 s56, s56, s40
	v_lshl_add_u64 v[136:137], s[54:55], 0, v[0:1]
	s_mov_b32 m0, s56
	s_nop 0
	global_load_lds_dwordx4 v[136:137], off
	v_lshl_add_u64 v[136:137], s[54:55], 0, v[130:131]
	s_add_i32 m0, s56, 0x2000
	s_nop 0
	global_load_lds_dwordx4 v[136:137], off
	s_waitcnt vmcnt(6)
	s_barrier

	v_mfma_f32_16x16x32_bf16 v[54:57], v[214:217], v[158:161], v[54:57]
	v_mfma_f32_16x16x32_bf16 v[50:53], v[222:225], v[158:161], v[50:53]
	v_mfma_f32_16x16x32_bf16 v[38:41], v[214:217], v[166:169], v[38:41]
	v_mfma_f32_16x16x32_bf16 v[34:37], v[222:225], v[166:169], v[34:37]
	v_mfma_f32_16x16x32_bf16 v[22:25], v[214:217], v[178:181], v[22:25]
	v_mfma_f32_16x16x32_bf16 v[18:21], v[222:225], v[178:181], v[18:21]
	v_mfma_f32_16x16x32_bf16 v[6:9], v[214:217], v[186:189], v[6:9]
	v_mfma_f32_16x16x32_bf16 v[2:5], v[222:225], v[186:189], v[2:5]
	v_mfma_f32_16x16x32_bf16 v[54:57], v[218:221], v[162:165], v[54:57]
	v_mfma_f32_16x16x32_bf16 v[50:53], v[226:229], v[162:165], v[50:53]
	v_mfma_f32_16x16x32_bf16 v[38:41], v[218:221], v[170:173], v[38:41]
	v_mfma_f32_16x16x32_bf16 v[34:37], v[226:229], v[170:173], v[34:37]
	v_mfma_f32_16x16x32_bf16 v[22:25], v[218:221], v[182:185], v[22:25]
	v_mfma_f32_16x16x32_bf16 v[18:21], v[226:229], v[182:185], v[18:21]
	v_mfma_f32_16x16x32_bf16 v[6:9], v[218:221], v[210:213], v[6:9]
	v_mfma_f32_16x16x32_bf16 v[2:5], v[226:229], v[210:213], v[2:5]

	s_add_i32 s23, s23, 2
	s_add_u32 s52, s52, 0x100
	s_addc_u32 s53, s53, 0
	s_add_u32 s90, s90, 0x100
	s_addc_u32 s22, s22, 0
	s_cmp_gt_u32 s23, 13
	s_barrier
	s_cbranch_scc0 .LBB0_960
	v_mul_f32_e32 v143, 0xbfb8aa3b, v126
	v_exp_f32_e32 v143, v143
	v_lshl_or_b32 v144, s64, 7, v140
	v_lshl_add_u32 v142, s65, 8, v138
	v_mov_b64_e32 v[136:137], s[12:13]
	v_add_f32_e32 v143, 1.0, v143
	v_rcp_f32_e32 v148, v143
	v_mul_f32_e32 v143, 0xbfb8aa3b, v127
	v_exp_f32_e32 v143, v143
	v_ashrrev_i32_e32 v145, 31, v144
	v_mad_i64_i32 v[146:147], s[22:23], v142, s89, v[136:137]
	v_add_f32_e32 v143, 1.0, v143
	v_rcp_f32_e32 v149, v143
	s_and_b64 vcc, exec, s[2:3]
	s_mov_b32 s64, s0
	s_mov_b32 s65, s4
	v_pk_mul_f32 v[126:127], v[126:127], v[148:149]
	s_mov_b64 s[54:55], s[18:19]
	v_pk_mul_f32 v[122:123], v[122:123], v[126:127]
	s_mov_b64 s[52:53], s[6:7]
	v_cvt_pk_bf16_f32 v126, v122, v123
	v_mul_f32_e32 v122, 0xbfb8aa3b, v128
	v_mul_f32_e32 v123, 0xbfb8aa3b, v129
	v_exp_f32_e32 v122, v122
	v_exp_f32_e32 v123, v123
	v_add_f32_e32 v122, 1.0, v122
	v_add_f32_e32 v123, 1.0, v123
	v_rcp_f32_e32 v122, v122
	v_rcp_f32_e32 v123, v123
	s_nop 0
	v_pk_mul_f32 v[122:123], v[128:129], v[122:123]
	s_nop 0
	v_pk_mul_f32 v[122:123], v[124:125], v[122:123]
	s_nop 0
	v_cvt_pk_bf16_f32 v127, v122, v123
	v_lshlrev_b64 v[122:123], 1, v[144:145]
	v_lshl_add_u64 v[124:125], v[146:147], 0, v[122:123]
	global_store_dwordx2 v[124:125], v[126:127], off
	v_mul_f32_e32 v126, 0xbfb8aa3b, v118
	v_mul_f32_e32 v127, 0xbfb8aa3b, v119
	v_exp_f32_e32 v126, v126
	v_exp_f32_e32 v127, v127
	v_add_f32_e32 v126, 1.0, v126
	v_add_f32_e32 v127, 1.0, v127
	v_rcp_f32_e32 v126, v126
	v_rcp_f32_e32 v127, v127
	s_nop 0
	v_pk_mul_f32 v[118:119], v[118:119], v[126:127]
	s_nop 0
	v_pk_mul_f32 v[114:115], v[114:115], v[118:119]
	s_nop 0
	v_cvt_pk_bf16_f32 v114, v114, v115
	v_mul_f32_e32 v115, 0xbfb8aa3b, v120
	v_exp_f32_e32 v115, v115
	s_nop 0
	v_add_f32_e32 v115, 1.0, v115
	v_rcp_f32_e32 v118, v115
	v_mul_f32_e32 v115, 0xbfb8aa3b, v121
	v_exp_f32_e32 v115, v115
	s_nop 0
	v_add_f32_e32 v115, 1.0, v115
	v_rcp_f32_e32 v119, v115
	s_nop 0
	v_pk_mul_f32 v[118:119], v[120:121], v[118:119]
	s_nop 0
	v_pk_mul_f32 v[116:117], v[116:117], v[118:119]
	s_nop 0
	v_cvt_pk_bf16_f32 v115, v116, v117
	v_mul_f32_e32 v116, 0xbfb8aa3b, v110
	v_mul_f32_e32 v117, 0xbfb8aa3b, v111
	v_exp_f32_e32 v116, v116
	v_exp_f32_e32 v117, v117
	global_store_dwordx2 v[124:125], v[114:115], off offset:128
	v_or_b32_e32 v114, 16, v142
	v_add_f32_e32 v116, 1.0, v116
	v_add_f32_e32 v117, 1.0, v117
	v_rcp_f32_e32 v116, v116
	v_rcp_f32_e32 v117, v117
	v_mad_i64_i32 v[114:115], s[22:23], v114, s89, v[136:137]
	v_pk_mul_f32 v[110:111], v[110:111], v[116:117]
	s_nop 0
	v_pk_mul_f32 v[106:107], v[106:107], v[110:111]
	s_nop 0
	v_cvt_pk_bf16_f32 v106, v106, v107
	v_mul_f32_e32 v107, 0xbfb8aa3b, v112
	v_exp_f32_e32 v107, v107
	s_nop 0
	v_add_f32_e32 v107, 1.0, v107
	v_rcp_f32_e32 v110, v107
	v_mul_f32_e32 v107, 0xbfb8aa3b, v113
	v_exp_f32_e32 v107, v107
	s_nop 0
	v_add_f32_e32 v107, 1.0, v107
	v_rcp_f32_e32 v111, v107
	s_nop 0
	v_pk_mul_f32 v[110:111], v[112:113], v[110:111]
	s_nop 0
	v_pk_mul_f32 v[108:109], v[108:109], v[110:111]
	s_nop 0
	v_cvt_pk_bf16_f32 v107, v108, v109
	v_lshl_add_u64 v[108:109], v[114:115], 0, v[122:123]
	global_store_dwordx2 v[108:109], v[106:107], off
	v_mul_f32_e32 v106, 0xbfb8aa3b, v102
	v_mul_f32_e32 v107, 0xbfb8aa3b, v103
	v_exp_f32_e32 v106, v106
	v_exp_f32_e32 v107, v107
	v_add_f32_e32 v106, 1.0, v106
	v_add_f32_e32 v107, 1.0, v107
	v_rcp_f32_e32 v106, v106
	v_rcp_f32_e32 v107, v107
	s_nop 0
	v_pk_mul_f32 v[102:103], v[102:103], v[106:107]
	s_nop 0
	v_pk_mul_f32 v[98:99], v[98:99], v[102:103]
	s_nop 0
	v_cvt_pk_bf16_f32 v98, v98, v99
	v_mul_f32_e32 v99, 0xbfb8aa3b, v104
	v_exp_f32_e32 v99, v99
	s_nop 0
	v_add_f32_e32 v99, 1.0, v99
	v_rcp_f32_e32 v102, v99
	v_mul_f32_e32 v99, 0xbfb8aa3b, v105
	v_exp_f32_e32 v99, v99
	s_nop 0
	v_add_f32_e32 v99, 1.0, v99
	v_rcp_f32_e32 v103, v99
	s_nop 0
	v_pk_mul_f32 v[102:103], v[104:105], v[102:103]
	s_nop 0
	v_pk_mul_f32 v[100:101], v[100:101], v[102:103]
	s_nop 0
	v_cvt_pk_bf16_f32 v99, v100, v101
	v_mul_f32_e32 v100, 0xbfb8aa3b, v94
	v_mul_f32_e32 v101, 0xbfb8aa3b, v95
	v_exp_f32_e32 v100, v100
	v_exp_f32_e32 v101, v101
	global_store_dwordx2 v[108:109], v[98:99], off offset:128
	v_or_b32_e32 v98, 32, v142
	v_add_f32_e32 v100, 1.0, v100
	v_add_f32_e32 v101, 1.0, v101
	v_rcp_f32_e32 v100, v100
	v_rcp_f32_e32 v101, v101
	v_mad_i64_i32 v[98:99], s[22:23], v98, s89, v[136:137]
	v_pk_mul_f32 v[94:95], v[94:95], v[100:101]
	s_nop 0
	v_pk_mul_f32 v[90:91], v[90:91], v[94:95]
	s_nop 0
	v_cvt_pk_bf16_f32 v90, v90, v91
	v_mul_f32_e32 v91, 0xbfb8aa3b, v96
	v_exp_f32_e32 v91, v91
	s_nop 0
	v_add_f32_e32 v91, 1.0, v91
	v_rcp_f32_e32 v94, v91
	v_mul_f32_e32 v91, 0xbfb8aa3b, v97
	v_exp_f32_e32 v91, v91
	s_nop 0
	v_add_f32_e32 v91, 1.0, v91
	v_rcp_f32_e32 v95, v91
	s_nop 0
	v_pk_mul_f32 v[94:95], v[96:97], v[94:95]
	s_nop 0
	v_pk_mul_f32 v[92:93], v[92:93], v[94:95]
	s_nop 0
	v_cvt_pk_bf16_f32 v91, v92, v93
	v_lshl_add_u64 v[92:93], v[98:99], 0, v[122:123]
	global_store_dwordx2 v[92:93], v[90:91], off
	v_mul_f32_e32 v90, 0xbfb8aa3b, v86
	v_mul_f32_e32 v91, 0xbfb8aa3b, v87
	v_exp_f32_e32 v90, v90
	v_exp_f32_e32 v91, v91
	v_add_f32_e32 v90, 1.0, v90
	v_add_f32_e32 v91, 1.0, v91
	v_rcp_f32_e32 v90, v90
	v_rcp_f32_e32 v91, v91
	s_nop 0
	v_pk_mul_f32 v[86:87], v[86:87], v[90:91]
	s_nop 0
	v_pk_mul_f32 v[82:83], v[82:83], v[86:87]
	s_nop 0
	v_cvt_pk_bf16_f32 v82, v82, v83
	v_mul_f32_e32 v83, 0xbfb8aa3b, v88
	v_exp_f32_e32 v83, v83
	s_nop 0
	v_add_f32_e32 v83, 1.0, v83
	v_rcp_f32_e32 v86, v83
	v_mul_f32_e32 v83, 0xbfb8aa3b, v89
	v_exp_f32_e32 v83, v83
	s_nop 0
	v_add_f32_e32 v83, 1.0, v83
	v_rcp_f32_e32 v87, v83
	s_nop 0
	v_pk_mul_f32 v[86:87], v[88:89], v[86:87]
	s_nop 0
	v_pk_mul_f32 v[84:85], v[84:85], v[86:87]
	s_nop 0
	v_cvt_pk_bf16_f32 v83, v84, v85
	v_mul_f32_e32 v84, 0xbfb8aa3b, v78
	v_mul_f32_e32 v85, 0xbfb8aa3b, v79
	v_exp_f32_e32 v84, v84
	v_exp_f32_e32 v85, v85
	global_store_dwordx2 v[92:93], v[82:83], off offset:128
	v_or_b32_e32 v82, 48, v142
	v_add_f32_e32 v84, 1.0, v84
	v_add_f32_e32 v85, 1.0, v85
	v_rcp_f32_e32 v84, v84
	v_rcp_f32_e32 v85, v85
	v_mad_i64_i32 v[82:83], s[22:23], v82, s89, v[136:137]
	v_pk_mul_f32 v[78:79], v[78:79], v[84:85]
	s_nop 0
	v_pk_mul_f32 v[74:75], v[74:75], v[78:79]
	s_nop 0
	v_cvt_pk_bf16_f32 v74, v74, v75
	v_mul_f32_e32 v75, 0xbfb8aa3b, v80
	v_exp_f32_e32 v75, v75
	s_nop 0
	v_add_f32_e32 v75, 1.0, v75
	v_rcp_f32_e32 v78, v75
	v_mul_f32_e32 v75, 0xbfb8aa3b, v81
	v_exp_f32_e32 v75, v75
	s_nop 0
	v_add_f32_e32 v75, 1.0, v75
	v_rcp_f32_e32 v79, v75
	s_nop 0
	v_pk_mul_f32 v[78:79], v[80:81], v[78:79]
	s_nop 0
	v_pk_mul_f32 v[76:77], v[76:77], v[78:79]
	s_nop 0
	v_cvt_pk_bf16_f32 v75, v76, v77
	v_lshl_add_u64 v[76:77], v[82:83], 0, v[122:123]
	global_store_dwordx2 v[76:77], v[74:75], off
	v_mul_f32_e32 v74, 0xbfb8aa3b, v70
	v_mul_f32_e32 v75, 0xbfb8aa3b, v71
	v_exp_f32_e32 v74, v74
	v_exp_f32_e32 v75, v75
	v_add_f32_e32 v74, 1.0, v74
	v_add_f32_e32 v75, 1.0, v75
	v_rcp_f32_e32 v74, v74
	v_rcp_f32_e32 v75, v75
	s_nop 0
	v_pk_mul_f32 v[70:71], v[70:71], v[74:75]
	s_nop 0
	v_pk_mul_f32 v[66:67], v[66:67], v[70:71]
	s_nop 0
	v_cvt_pk_bf16_f32 v66, v66, v67
	v_mul_f32_e32 v67, 0xbfb8aa3b, v72
	v_exp_f32_e32 v67, v67
	s_nop 0
	v_add_f32_e32 v67, 1.0, v67
	v_rcp_f32_e32 v70, v67
	v_mul_f32_e32 v67, 0xbfb8aa3b, v73
	v_exp_f32_e32 v67, v67
	s_nop 0
	v_add_f32_e32 v67, 1.0, v67
	v_rcp_f32_e32 v71, v67
	s_nop 0
	v_pk_mul_f32 v[70:71], v[72:73], v[70:71]
	s_nop 0
	v_pk_mul_f32 v[68:69], v[68:69], v[70:71]
	s_nop 0
	v_cvt_pk_bf16_f32 v67, v68, v69
	v_mul_f32_e32 v68, 0xbfb8aa3b, v62
	v_mul_f32_e32 v69, 0xbfb8aa3b, v63
	v_exp_f32_e32 v68, v68
	v_exp_f32_e32 v69, v69
	global_store_dwordx2 v[76:77], v[66:67], off offset:128
	v_add_u32_e32 v66, 0x80, v142
	v_add_f32_e32 v68, 1.0, v68
	v_add_f32_e32 v69, 1.0, v69
	v_rcp_f32_e32 v68, v68
	v_rcp_f32_e32 v69, v69
	v_mad_i64_i32 v[66:67], s[22:23], v66, s89, v[136:137]
	v_pk_mul_f32 v[62:63], v[62:63], v[68:69]
	s_nop 0
	v_pk_mul_f32 v[58:59], v[58:59], v[62:63]
	s_nop 0
	v_cvt_pk_bf16_f32 v58, v58, v59
	v_mul_f32_e32 v59, 0xbfb8aa3b, v64
	v_exp_f32_e32 v59, v59
	s_nop 0
	v_add_f32_e32 v59, 1.0, v59
	v_rcp_f32_e32 v62, v59
	v_mul_f32_e32 v59, 0xbfb8aa3b, v65
	v_exp_f32_e32 v59, v59
	s_nop 0
	v_add_f32_e32 v59, 1.0, v59
	v_rcp_f32_e32 v63, v59
	s_nop 0
	v_pk_mul_f32 v[62:63], v[64:65], v[62:63]
	s_nop 0
	v_pk_mul_f32 v[60:61], v[60:61], v[62:63]
	s_nop 0
	v_cvt_pk_bf16_f32 v59, v60, v61
	v_lshl_add_u64 v[60:61], v[66:67], 0, v[122:123]
	global_store_dwordx2 v[60:61], v[58:59], off
	v_mul_f32_e32 v58, 0xbfb8aa3b, v54
	v_mul_f32_e32 v59, 0xbfb8aa3b, v55
	v_exp_f32_e32 v58, v58
	v_exp_f32_e32 v59, v59
	v_add_f32_e32 v58, 1.0, v58
	v_add_f32_e32 v59, 1.0, v59
	v_rcp_f32_e32 v58, v58
	v_rcp_f32_e32 v59, v59
	s_nop 0
	v_pk_mul_f32 v[54:55], v[54:55], v[58:59]
	s_nop 0
	v_pk_mul_f32 v[50:51], v[50:51], v[54:55]
	s_nop 0
	v_cvt_pk_bf16_f32 v50, v50, v51
	v_mul_f32_e32 v51, 0xbfb8aa3b, v56
	v_exp_f32_e32 v51, v51
	s_nop 0
	v_add_f32_e32 v51, 1.0, v51
	v_rcp_f32_e32 v54, v51
	v_mul_f32_e32 v51, 0xbfb8aa3b, v57
	v_exp_f32_e32 v51, v51
	s_nop 0
	v_add_f32_e32 v51, 1.0, v51
	v_rcp_f32_e32 v55, v51
	s_nop 0
	v_pk_mul_f32 v[54:55], v[56:57], v[54:55]
	s_nop 0
	v_pk_mul_f32 v[52:53], v[52:53], v[54:55]
	s_nop 0
	v_cvt_pk_bf16_f32 v51, v52, v53
	v_mul_f32_e32 v52, 0xbfb8aa3b, v46
	v_mul_f32_e32 v53, 0xbfb8aa3b, v47
	v_exp_f32_e32 v52, v52
	v_exp_f32_e32 v53, v53
	global_store_dwordx2 v[60:61], v[50:51], off offset:128
	v_add_u32_e32 v50, 0x90, v142
	v_add_f32_e32 v52, 1.0, v52
	v_add_f32_e32 v53, 1.0, v53
	v_rcp_f32_e32 v52, v52
	v_rcp_f32_e32 v53, v53
	v_mad_i64_i32 v[50:51], s[22:23], v50, s89, v[136:137]
	v_pk_mul_f32 v[46:47], v[46:47], v[52:53]
	s_nop 0
	v_pk_mul_f32 v[42:43], v[42:43], v[46:47]
	s_nop 0
	v_cvt_pk_bf16_f32 v42, v42, v43
	v_mul_f32_e32 v43, 0xbfb8aa3b, v48
	v_exp_f32_e32 v43, v43
	s_nop 0
	v_add_f32_e32 v43, 1.0, v43
	v_rcp_f32_e32 v46, v43
	v_mul_f32_e32 v43, 0xbfb8aa3b, v49
	v_exp_f32_e32 v43, v43
	s_nop 0
	v_add_f32_e32 v43, 1.0, v43
	v_rcp_f32_e32 v47, v43
	s_nop 0
	v_pk_mul_f32 v[46:47], v[48:49], v[46:47]
	s_nop 0
	v_pk_mul_f32 v[44:45], v[44:45], v[46:47]
	s_nop 0
	v_cvt_pk_bf16_f32 v43, v44, v45
	v_lshl_add_u64 v[44:45], v[50:51], 0, v[122:123]
	global_store_dwordx2 v[44:45], v[42:43], off
	v_mul_f32_e32 v42, 0xbfb8aa3b, v38
	v_mul_f32_e32 v43, 0xbfb8aa3b, v39
	v_exp_f32_e32 v42, v42
	v_exp_f32_e32 v43, v43
	v_add_f32_e32 v42, 1.0, v42
	v_add_f32_e32 v43, 1.0, v43
	v_rcp_f32_e32 v42, v42
	v_rcp_f32_e32 v43, v43
	s_nop 0
	v_pk_mul_f32 v[38:39], v[38:39], v[42:43]
	s_nop 0
	v_pk_mul_f32 v[34:35], v[34:35], v[38:39]
	s_nop 0
	v_cvt_pk_bf16_f32 v34, v34, v35
	v_mul_f32_e32 v35, 0xbfb8aa3b, v40
	v_exp_f32_e32 v35, v35
	s_nop 0
	v_add_f32_e32 v35, 1.0, v35
	v_rcp_f32_e32 v38, v35
	v_mul_f32_e32 v35, 0xbfb8aa3b, v41
	v_exp_f32_e32 v35, v35
	s_nop 0
	v_add_f32_e32 v35, 1.0, v35
	v_rcp_f32_e32 v39, v35
	s_nop 0
	v_pk_mul_f32 v[38:39], v[40:41], v[38:39]
	s_nop 0
	v_pk_mul_f32 v[36:37], v[36:37], v[38:39]
	s_nop 0
	v_cvt_pk_bf16_f32 v35, v36, v37
	v_mul_f32_e32 v36, 0xbfb8aa3b, v30
	v_mul_f32_e32 v37, 0xbfb8aa3b, v31
	v_exp_f32_e32 v36, v36
	v_exp_f32_e32 v37, v37
	global_store_dwordx2 v[44:45], v[34:35], off offset:128
	v_add_u32_e32 v34, 0xa0, v142
	v_add_f32_e32 v36, 1.0, v36
	v_add_f32_e32 v37, 1.0, v37
	v_rcp_f32_e32 v36, v36
	v_rcp_f32_e32 v37, v37
	v_mad_i64_i32 v[34:35], s[22:23], v34, s89, v[136:137]
	v_pk_mul_f32 v[30:31], v[30:31], v[36:37]
	s_nop 0
	v_pk_mul_f32 v[26:27], v[26:27], v[30:31]
	s_nop 0
	v_cvt_pk_bf16_f32 v26, v26, v27
	v_mul_f32_e32 v27, 0xbfb8aa3b, v32
	v_exp_f32_e32 v27, v27
	s_nop 0
	v_add_f32_e32 v27, 1.0, v27
	v_rcp_f32_e32 v30, v27
	v_mul_f32_e32 v27, 0xbfb8aa3b, v33
	v_exp_f32_e32 v27, v27
	s_nop 0
	v_add_f32_e32 v27, 1.0, v27
	v_rcp_f32_e32 v31, v27
	s_nop 0
	v_pk_mul_f32 v[30:31], v[32:33], v[30:31]
	s_nop 0
	v_pk_mul_f32 v[28:29], v[28:29], v[30:31]
	s_nop 0
	v_cvt_pk_bf16_f32 v27, v28, v29
	v_lshl_add_u64 v[28:29], v[34:35], 0, v[122:123]
	global_store_dwordx2 v[28:29], v[26:27], off
	v_mul_f32_e32 v26, 0xbfb8aa3b, v22
	v_mul_f32_e32 v27, 0xbfb8aa3b, v23
	v_exp_f32_e32 v26, v26
	v_exp_f32_e32 v27, v27
	v_add_f32_e32 v26, 1.0, v26
	v_add_f32_e32 v27, 1.0, v27
	v_rcp_f32_e32 v26, v26
	v_rcp_f32_e32 v27, v27
	s_nop 0
	v_pk_mul_f32 v[22:23], v[22:23], v[26:27]
	s_nop 0
	v_pk_mul_f32 v[18:19], v[18:19], v[22:23]
	s_nop 0
	v_cvt_pk_bf16_f32 v18, v18, v19
	v_mul_f32_e32 v19, 0xbfb8aa3b, v24
	v_exp_f32_e32 v19, v19
	s_nop 0
	v_add_f32_e32 v19, 1.0, v19
	v_rcp_f32_e32 v22, v19
	v_mul_f32_e32 v19, 0xbfb8aa3b, v25
	v_exp_f32_e32 v19, v19
	s_nop 0
	v_add_f32_e32 v19, 1.0, v19
	v_rcp_f32_e32 v23, v19
	s_nop 0
	v_pk_mul_f32 v[22:23], v[24:25], v[22:23]
	s_nop 0
	v_pk_mul_f32 v[20:21], v[20:21], v[22:23]
	s_nop 0
	v_cvt_pk_bf16_f32 v19, v20, v21
	v_mul_f32_e32 v20, 0xbfb8aa3b, v14
	v_mul_f32_e32 v21, 0xbfb8aa3b, v15
	v_exp_f32_e32 v20, v20
	v_exp_f32_e32 v21, v21
	global_store_dwordx2 v[28:29], v[18:19], off offset:128
	v_add_u32_e32 v18, 0xb0, v142
	v_add_f32_e32 v20, 1.0, v20
	v_add_f32_e32 v21, 1.0, v21
	v_rcp_f32_e32 v20, v20
	v_rcp_f32_e32 v21, v21
	v_mad_i64_i32 v[18:19], s[22:23], v18, s89, v[136:137]
	v_pk_mul_f32 v[14:15], v[14:15], v[20:21]
	s_nop 0
	v_pk_mul_f32 v[10:11], v[10:11], v[14:15]
	s_nop 0
	v_cvt_pk_bf16_f32 v10, v10, v11
	v_mul_f32_e32 v11, 0xbfb8aa3b, v16
	v_exp_f32_e32 v11, v11
	s_nop 0
	v_add_f32_e32 v11, 1.0, v11
	v_rcp_f32_e32 v14, v11
	v_mul_f32_e32 v11, 0xbfb8aa3b, v17
	v_exp_f32_e32 v11, v11
	s_nop 0
	v_add_f32_e32 v11, 1.0, v11
	v_rcp_f32_e32 v15, v11
	s_nop 0
	v_pk_mul_f32 v[14:15], v[16:17], v[14:15]
	s_nop 0
	v_pk_mul_f32 v[12:13], v[12:13], v[14:15]
	s_nop 0
	v_cvt_pk_bf16_f32 v11, v12, v13
	v_lshl_add_u64 v[12:13], v[18:19], 0, v[122:123]
	global_store_dwordx2 v[12:13], v[10:11], off
	v_mul_f32_e32 v10, 0xbfb8aa3b, v6
	v_mul_f32_e32 v11, 0xbfb8aa3b, v7
	v_exp_f32_e32 v10, v10
	v_exp_f32_e32 v11, v11
	v_add_f32_e32 v10, 1.0, v10
	v_add_f32_e32 v11, 1.0, v11
	v_rcp_f32_e32 v10, v10
	v_rcp_f32_e32 v11, v11
	s_nop 0
	v_pk_mul_f32 v[6:7], v[6:7], v[10:11]
	s_nop 0
	v_pk_mul_f32 v[2:3], v[2:3], v[6:7]
	s_nop 0
	v_cvt_pk_bf16_f32 v2, v2, v3
	v_mul_f32_e32 v3, 0xbfb8aa3b, v8
	v_exp_f32_e32 v3, v3
	s_nop 0
	v_add_f32_e32 v3, 1.0, v3
	v_rcp_f32_e32 v6, v3
	v_mul_f32_e32 v3, 0xbfb8aa3b, v9
	v_exp_f32_e32 v3, v3
	s_nop 0
	v_add_f32_e32 v3, 1.0, v3
	v_rcp_f32_e32 v7, v3
	s_nop 0
	v_pk_mul_f32 v[6:7], v[8:9], v[6:7]
	s_nop 0
	v_pk_mul_f32 v[4:5], v[4:5], v[6:7]
	s_nop 0
	v_cvt_pk_bf16_f32 v3, v4, v5
	global_store_dwordx2 v[12:13], v[2:3], off offset:128
	s_cbranch_vccz .LBB0_957
	s_waitcnt vmcnt(0)
	v_readlane_b32 s64, v254, 62
	s_cmpk_gt_u32 s14, 0xff
	v_readlane_b32 s65, v254, 63
	s_cbranch_scc1 .LBB0_964
	s_barrier

.LBB0_1049:
	s_add_u32 s52, s18, 0x100
	s_addc_u32 s53, s19, 0
	s_add_i32 s68, 0, 0x10000
	v_add_u32_e32 v78, s68, v165
	ds_read_b128 v[66:69], v78
	ds_read_b128 v[70:73], v78 offset:1024
	ds_read_b128 v[74:77], v78 offset:2048
	ds_read_b128 v[78:81], v78 offset:3072
	s_cmp_eq_u32 s94, 40
	s_cselect_b32 s57, s5, s53
	s_cselect_b32 s56, s4, s52
	s_cselect_b32 s55, s1, s23
	s_cselect_b32 s54, s0, s22
	v_lshl_add_u64 v[172:173], s[18:19], 0, v[148:149]
	s_add_i32 m0, s41, 0xc000
	ds_read_b128 v[152:155], v167
	ds_read_b128 v[156:159], v167 offset:1024
	ds_read_b128 v[160:163], v167 offset:2048
	ds_read_b128 v[168:171], v167 offset:3072
	ds_read_b128 v[178:181], v167 offset:4096
	ds_read_b128 v[182:185], v167 offset:5120
	ds_read_b128 v[186:189], v167 offset:6144
	ds_read_b128 v[202:205], v167 offset:7168
	global_load_lds_dwordx4 v[172:173], off
	v_lshl_add_u64 v[172:173], s[18:19], 0, v[150:151]
	s_add_i32 m0, s41, 0xe000
	s_nop 0
	global_load_lds_dwordx4 v[172:173], off
	s_waitcnt lgkmcnt(8)
	s_barrier
	s_waitcnt lgkmcnt(0)


	v_mfma_f32_16x16x32_bf16 v[142:145], v[66:69], v[152:155], v[142:145]
	v_mfma_f32_16x16x32_bf16 v[138:141], v[74:77], v[152:155], v[138:141]
	v_mfma_f32_16x16x32_bf16 v[134:137], v[66:69], v[160:163], v[134:137]
	v_mfma_f32_16x16x32_bf16 v[130:133], v[74:77], v[160:163], v[130:133]
	v_mfma_f32_16x16x32_bf16 v[122:125], v[66:69], v[178:181], v[122:125]
	v_mfma_f32_16x16x32_bf16 v[114:117], v[74:77], v[178:181], v[114:117]
	v_mfma_f32_16x16x32_bf16 v[106:109], v[66:69], v[186:189], v[106:109]
	v_mfma_f32_16x16x32_bf16 v[98:101], v[74:77], v[186:189], v[98:101]
	v_mfma_f32_16x16x32_bf16 v[142:145], v[70:73], v[156:159], v[142:145]
	v_mfma_f32_16x16x32_bf16 v[138:141], v[78:81], v[156:159], v[138:141]
	v_mfma_f32_16x16x32_bf16 v[134:137], v[70:73], v[168:171], v[134:137]
	v_mfma_f32_16x16x32_bf16 v[130:133], v[78:81], v[168:171], v[130:133]
	v_mfma_f32_16x16x32_bf16 v[122:125], v[70:73], v[182:185], v[122:125]
	v_mfma_f32_16x16x32_bf16 v[114:117], v[78:81], v[182:185], v[114:117]
	v_mfma_f32_16x16x32_bf16 v[106:109], v[70:73], v[202:205], v[106:109]
	v_mfma_f32_16x16x32_bf16 v[98:101], v[78:81], v[202:205], v[98:101]

	s_barrier
	s_add_i32 s69, 0, 0x14000
	v_add_u32_e32 v172, s69, v165
	s_add_i32 s18, s68, s40
	ds_read_b128 v[210:213], v172
	ds_read_b128 v[214:217], v172 offset:1024
	ds_read_b128 v[218:221], v172 offset:2048
	ds_read_b128 v[222:225], v172 offset:3072
	v_lshl_add_u64 v[172:173], s[54:55], 0, v[0:1]
	s_mov_b32 m0, s18
	v_lshl_add_u64 v[190:191], s[54:55], 0, v[146:147]
	global_load_lds_dwordx4 v[172:173], off
	s_add_i32 m0, s18, 0x2000
	s_nop 0
	global_load_lds_dwordx4 v[190:191], off
	s_barrier
	s_waitcnt lgkmcnt(0)


	v_mfma_f32_16x16x32_bf16 v[126:129], v[210:213], v[152:155], v[126:129]
	v_mfma_f32_16x16x32_bf16 v[118:121], v[218:221], v[152:155], v[118:121]
	v_mfma_f32_16x16x32_bf16 v[110:113], v[210:213], v[160:163], v[110:113]
	v_mfma_f32_16x16x32_bf16 v[102:105], v[218:221], v[160:163], v[102:105]
	v_mfma_f32_16x16x32_bf16 v[94:97], v[210:213], v[178:181], v[94:97]
	v_mfma_f32_16x16x32_bf16 v[90:93], v[218:221], v[178:181], v[90:93]
	v_mfma_f32_16x16x32_bf16 v[86:89], v[210:213], v[186:189], v[86:89]
	v_mfma_f32_16x16x32_bf16 v[82:85], v[218:221], v[186:189], v[82:85]
	v_mfma_f32_16x16x32_bf16 v[126:129], v[214:217], v[156:159], v[126:129]
	v_mfma_f32_16x16x32_bf16 v[118:121], v[222:225], v[156:159], v[118:121]
	v_mfma_f32_16x16x32_bf16 v[110:113], v[214:217], v[168:171], v[110:113]
	v_mfma_f32_16x16x32_bf16 v[102:105], v[222:225], v[168:171], v[102:105]
	v_mfma_f32_16x16x32_bf16 v[94:97], v[214:217], v[182:185], v[94:97]
	v_mfma_f32_16x16x32_bf16 v[90:93], v[222:225], v[182:185], v[90:93]
	v_mfma_f32_16x16x32_bf16 v[86:89], v[214:217], v[202:205], v[86:89]
	v_mfma_f32_16x16x32_bf16 v[82:85], v[222:225], v[202:205], v[82:85]

	s_mov_b32 m0, s41
	v_lshl_add_u64 v[226:227], s[56:57], 0, v[0:1]
	s_barrier
	ds_read_b128 v[152:155], v167 offset:16384
	ds_read_b128 v[156:159], v167 offset:17408
	ds_read_b128 v[160:163], v167 offset:18432
	ds_read_b128 v[168:171], v167 offset:19456
	ds_read_b128 v[178:181], v167 offset:20480
	ds_read_b128 v[182:185], v167 offset:21504
	ds_read_b128 v[186:189], v167 offset:22528
	ds_read_b128 v[202:205], v167 offset:23552
	global_load_lds_dwordx4 v[226:227], off
	v_lshl_add_u64 v[228:229], s[56:57], 0, v[146:147]
	s_mov_b32 m0, s42
	s_nop 0
	global_load_lds_dwordx4 v[228:229], off
	s_barrier
	s_waitcnt lgkmcnt(0)


	v_mfma_f32_16x16x32_bf16 v[62:65], v[66:69], v[152:155], v[62:65]
	v_mfma_f32_16x16x32_bf16 v[58:61], v[74:77], v[152:155], v[58:61]
	v_mfma_f32_16x16x32_bf16 v[54:57], v[66:69], v[160:163], v[54:57]
	v_mfma_f32_16x16x32_bf16 v[46:49], v[74:77], v[160:163], v[46:49]
	v_mfma_f32_16x16x32_bf16 v[38:41], v[66:69], v[178:181], v[38:41]
	v_mfma_f32_16x16x32_bf16 v[30:33], v[74:77], v[178:181], v[30:33]
	v_mfma_f32_16x16x32_bf16 v[22:25], v[66:69], v[186:189], v[22:25]
	v_mfma_f32_16x16x32_bf16 v[14:17], v[74:77], v[186:189], v[14:17]
	v_mfma_f32_16x16x32_bf16 v[62:65], v[70:73], v[156:159], v[62:65]
	v_mfma_f32_16x16x32_bf16 v[58:61], v[78:81], v[156:159], v[58:61]
	v_mfma_f32_16x16x32_bf16 v[54:57], v[70:73], v[168:171], v[54:57]
	v_mfma_f32_16x16x32_bf16 v[46:49], v[78:81], v[168:171], v[46:49]
	v_mfma_f32_16x16x32_bf16 v[38:41], v[70:73], v[182:185], v[38:41]
	v_mfma_f32_16x16x32_bf16 v[30:33], v[78:81], v[182:185], v[30:33]
	v_mfma_f32_16x16x32_bf16 v[22:25], v[70:73], v[202:205], v[22:25]
	v_mfma_f32_16x16x32_bf16 v[14:17], v[78:81], v[202:205], v[14:17]

	s_barrier
	s_add_u32 s18, s54, 0xb0000
	s_addc_u32 s19, s55, 0
	s_add_i32 s68, s69, s40
	v_lshl_add_u64 v[66:67], s[18:19], 0, v[0:1]
	s_mov_b32 m0, s68
	s_nop 0
	global_load_lds_dwordx4 v[66:67], off
	v_lshl_add_u64 v[66:67], s[18:19], 0, v[146:147]
	s_add_i32 m0, s68, 0x2000
	s_nop 0
	global_load_lds_dwordx4 v[66:67], off
	s_waitcnt vmcnt(6)
	s_barrier

	v_mfma_f32_16x16x32_bf16 v[50:53], v[210:213], v[152:155], v[50:53]
	v_mfma_f32_16x16x32_bf16 v[42:45], v[218:221], v[152:155], v[42:45]
	v_mfma_f32_16x16x32_bf16 v[34:37], v[210:213], v[160:163], v[34:37]
	v_mfma_f32_16x16x32_bf16 v[26:29], v[218:221], v[160:163], v[26:29]
	v_mfma_f32_16x16x32_bf16 v[18:21], v[210:213], v[178:181], v[18:21]
	v_mfma_f32_16x16x32_bf16 v[10:13], v[218:221], v[178:181], v[10:13]
	v_mfma_f32_16x16x32_bf16 v[6:9], v[210:213], v[186:189], v[6:9]
	v_mfma_f32_16x16x32_bf16 v[2:5], v[218:221], v[186:189], v[2:5]
	v_mfma_f32_16x16x32_bf16 v[50:53], v[214:217], v[156:159], v[50:53]
	v_mfma_f32_16x16x32_bf16 v[42:45], v[222:225], v[156:159], v[42:45]
	v_mfma_f32_16x16x32_bf16 v[34:37], v[214:217], v[168:171], v[34:37]
	v_mfma_f32_16x16x32_bf16 v[26:29], v[222:225], v[168:171], v[26:29]
	v_mfma_f32_16x16x32_bf16 v[18:21], v[214:217], v[182:185], v[18:21]
	v_mfma_f32_16x16x32_bf16 v[10:13], v[222:225], v[182:185], v[10:13]
	v_mfma_f32_16x16x32_bf16 v[6:9], v[214:217], v[202:205], v[6:9]
	v_mfma_f32_16x16x32_bf16 v[2:5], v[222:225], v[202:205], v[2:5]

	s_add_i32 s68, 0, 0x18000
	v_add_u32_e32 v78, s68, v165
	s_barrier
	ds_read_b128 v[66:69], v78
	ds_read_b128 v[70:73], v78 offset:1024
	ds_read_b128 v[74:77], v78 offset:2048
	ds_read_b128 v[78:81], v78 offset:3072
	s_add_u32 s18, s56, 0xb0000
	s_addc_u32 s19, s57, 0
	s_mov_b32 m0, s43
	v_lshl_add_u64 v[210:211], s[18:19], 0, v[0:1]
	ds_read_b128 v[152:155], v167 offset:32768
	ds_read_b128 v[156:159], v167 offset:33792
	ds_read_b128 v[160:163], v167 offset:34816
	ds_read_b128 v[168:171], v167 offset:35840
	ds_read_b128 v[178:181], v167 offset:36864
	ds_read_b128 v[182:185], v167 offset:37888
	ds_read_b128 v[186:189], v167 offset:38912
	ds_read_b128 v[202:205], v167 offset:39936
	global_load_lds_dwordx4 v[210:211], off
	v_lshl_add_u64 v[210:211], s[18:19], 0, v[146:147]
	s_mov_b32 m0, s58
	s_nop 0
	global_load_lds_dwordx4 v[210:211], off
	s_waitcnt lgkmcnt(8)
	s_barrier
	s_waitcnt lgkmcnt(0)


	v_mfma_f32_16x16x32_bf16 v[142:145], v[66:69], v[152:155], v[142:145]
	v_mfma_f32_16x16x32_bf16 v[138:141], v[74:77], v[152:155], v[138:141]
	v_mfma_f32_16x16x32_bf16 v[134:137], v[66:69], v[160:163], v[134:137]
	v_mfma_f32_16x16x32_bf16 v[130:133], v[74:77], v[160:163], v[130:133]
	v_mfma_f32_16x16x32_bf16 v[122:125], v[66:69], v[178:181], v[122:125]
	v_mfma_f32_16x16x32_bf16 v[114:117], v[74:77], v[178:181], v[114:117]
	v_mfma_f32_16x16x32_bf16 v[106:109], v[66:69], v[186:189], v[106:109]
	v_mfma_f32_16x16x32_bf16 v[98:101], v[74:77], v[186:189], v[98:101]
	v_mfma_f32_16x16x32_bf16 v[142:145], v[70:73], v[156:159], v[142:145]
	v_mfma_f32_16x16x32_bf16 v[138:141], v[78:81], v[156:159], v[138:141]
	v_mfma_f32_16x16x32_bf16 v[134:137], v[70:73], v[168:171], v[134:137]
	v_mfma_f32_16x16x32_bf16 v[130:133], v[78:81], v[168:171], v[130:133]
	v_mfma_f32_16x16x32_bf16 v[122:125], v[70:73], v[182:185], v[122:125]
	v_mfma_f32_16x16x32_bf16 v[114:117], v[78:81], v[182:185], v[114:117]
	v_mfma_f32_16x16x32_bf16 v[106:109], v[70:73], v[202:205], v[106:109]
	v_mfma_f32_16x16x32_bf16 v[98:101], v[78:81], v[202:205], v[98:101]

	s_barrier
	s_add_i32 s56, 0, 0x1c000
	s_add_i32 s18, s68, s40
	v_add_u32_e32 v209, s56, v165
	v_lshl_add_u64 v[172:173], v[172:173], 0, s[60:61]
	s_mov_b32 m0, s18
	ds_read_b128 v[210:213], v209
	ds_read_b128 v[214:217], v209 offset:1024
	ds_read_b128 v[218:221], v209 offset:2048
	ds_read_b128 v[222:225], v209 offset:3072
	global_load_lds_dwordx4 v[172:173], off
	v_lshl_add_u64 v[172:173], v[190:191], 0, s[60:61]
	s_add_i32 m0, s18, 0x2000
	s_nop 0
	global_load_lds_dwordx4 v[172:173], off
	s_barrier
	s_waitcnt lgkmcnt(0)


	v_mfma_f32_16x16x32_bf16 v[126:129], v[210:213], v[152:155], v[126:129]
	v_mfma_f32_16x16x32_bf16 v[118:121], v[218:221], v[152:155], v[118:121]
	v_mfma_f32_16x16x32_bf16 v[110:113], v[210:213], v[160:163], v[110:113]
	v_mfma_f32_16x16x32_bf16 v[102:105], v[218:221], v[160:163], v[102:105]
	v_mfma_f32_16x16x32_bf16 v[94:97], v[210:213], v[178:181], v[94:97]
	v_mfma_f32_16x16x32_bf16 v[90:93], v[218:221], v[178:181], v[90:93]
	v_mfma_f32_16x16x32_bf16 v[86:89], v[210:213], v[186:189], v[86:89]
	v_mfma_f32_16x16x32_bf16 v[82:85], v[218:221], v[186:189], v[82:85]
	v_mfma_f32_16x16x32_bf16 v[126:129], v[214:217], v[156:159], v[126:129]
	v_mfma_f32_16x16x32_bf16 v[118:121], v[222:225], v[156:159], v[118:121]
	v_mfma_f32_16x16x32_bf16 v[110:113], v[214:217], v[168:171], v[110:113]
	v_mfma_f32_16x16x32_bf16 v[102:105], v[222:225], v[168:171], v[102:105]
	v_mfma_f32_16x16x32_bf16 v[94:97], v[214:217], v[182:185], v[94:97]
	v_mfma_f32_16x16x32_bf16 v[90:93], v[222:225], v[182:185], v[90:93]
	v_mfma_f32_16x16x32_bf16 v[86:89], v[214:217], v[202:205], v[86:89]
	v_mfma_f32_16x16x32_bf16 v[82:85], v[222:225], v[202:205], v[82:85]

	s_mov_b32 m0, s63
	v_lshl_add_u64 v[172:173], v[226:227], 0, s[60:61]
	s_barrier
	ds_read_b128 v[152:155], v167 offset:49152
	ds_read_b128 v[156:159], v167 offset:50176
	ds_read_b128 v[160:163], v167 offset:51200
	ds_read_b128 v[168:171], v167 offset:52224
	ds_read_b128 v[178:181], v167 offset:53248
	ds_read_b128 v[182:185], v167 offset:54272
	ds_read_b128 v[186:189], v167 offset:55296
	ds_read_b128 v[202:205], v167 offset:56320
	global_load_lds_dwordx4 v[172:173], off
	v_lshl_add_u64 v[172:173], v[228:229], 0, s[60:61]
	s_mov_b32 m0, s64
	s_nop 0
	global_load_lds_dwordx4 v[172:173], off
	s_barrier
	s_waitcnt lgkmcnt(0)


	v_mfma_f32_16x16x32_bf16 v[62:65], v[66:69], v[152:155], v[62:65]
	v_mfma_f32_16x16x32_bf16 v[58:61], v[74:77], v[152:155], v[58:61]
	v_mfma_f32_16x16x32_bf16 v[54:57], v[66:69], v[160:163], v[54:57]
	v_mfma_f32_16x16x32_bf16 v[46:49], v[74:77], v[160:163], v[46:49]
	v_mfma_f32_16x16x32_bf16 v[38:41], v[66:69], v[178:181], v[38:41]
	v_mfma_f32_16x16x32_bf16 v[30:33], v[74:77], v[178:181], v[30:33]
	v_mfma_f32_16x16x32_bf16 v[22:25], v[66:69], v[186:189], v[22:25]
	v_mfma_f32_16x16x32_bf16 v[14:17], v[74:77], v[186:189], v[14:17]
	v_mfma_f32_16x16x32_bf16 v[62:65], v[70:73], v[156:159], v[62:65]
	v_mfma_f32_16x16x32_bf16 v[58:61], v[78:81], v[156:159], v[58:61]
	v_mfma_f32_16x16x32_bf16 v[54:57], v[70:73], v[168:171], v[54:57]
	v_mfma_f32_16x16x32_bf16 v[46:49], v[78:81], v[168:171], v[46:49]
	v_mfma_f32_16x16x32_bf16 v[38:41], v[70:73], v[182:185], v[38:41]
	v_mfma_f32_16x16x32_bf16 v[30:33], v[78:81], v[182:185], v[30:33]
	v_mfma_f32_16x16x32_bf16 v[22:25], v[70:73], v[202:205], v[22:25]
	v_mfma_f32_16x16x32_bf16 v[14:17], v[78:81], v[202:205], v[14:17]

	s_barrier
	s_add_u32 s18, s54, 0xb0080
	s_addc_u32 s19, s55, 0
	s_add_i32 s54, s56, s40
	v_lshl_add_u64 v[66:67], s[18:19], 0, v[0:1]
	s_mov_b32 m0, s54
	s_nop 0
	global_load_lds_dwordx4 v[66:67], off
	v_lshl_add_u64 v[66:67], s[18:19], 0, v[146:147]
	s_add_i32 m0, s54, 0x2000
	s_nop 0
	global_load_lds_dwordx4 v[66:67], off
	s_waitcnt vmcnt(6)
	s_barrier

	v_mfma_f32_16x16x32_bf16 v[50:53], v[210:213], v[152:155], v[50:53]
	v_mfma_f32_16x16x32_bf16 v[42:45], v[218:221], v[152:155], v[42:45]
	v_mfma_f32_16x16x32_bf16 v[34:37], v[210:213], v[160:163], v[34:37]
	v_mfma_f32_16x16x32_bf16 v[26:29], v[218:221], v[160:163], v[26:29]
	v_mfma_f32_16x16x32_bf16 v[18:21], v[210:213], v[178:181], v[18:21]
	v_mfma_f32_16x16x32_bf16 v[10:13], v[218:221], v[178:181], v[10:13]
	v_mfma_f32_16x16x32_bf16 v[6:9], v[210:213], v[186:189], v[6:9]
	v_mfma_f32_16x16x32_bf16 v[2:5], v[218:221], v[186:189], v[2:5]
	v_mfma_f32_16x16x32_bf16 v[50:53], v[214:217], v[156:159], v[50:53]
	v_mfma_f32_16x16x32_bf16 v[42:45], v[222:225], v[156:159], v[42:45]
	v_mfma_f32_16x16x32_bf16 v[34:37], v[214:217], v[168:171], v[34:37]
	v_mfma_f32_16x16x32_bf16 v[26:29], v[222:225], v[168:171], v[26:29]
	v_mfma_f32_16x16x32_bf16 v[18:21], v[214:217], v[182:185], v[18:21]
	v_mfma_f32_16x16x32_bf16 v[10:13], v[222:225], v[182:185], v[10:13]
	v_mfma_f32_16x16x32_bf16 v[6:9], v[214:217], v[202:205], v[6:9]
	v_mfma_f32_16x16x32_bf16 v[2:5], v[222:225], v[202:205], v[2:5]

	s_add_i32 s94, s94, 2
	s_add_u32 s22, s22, 0x100
	s_addc_u32 s23, s23, 0
	s_cmp_gt_u32 s94, 41
	s_mov_b64 s[18:19], s[52:53]
	s_barrier
	s_cbranch_scc0 .LBB0_1049
	s_sub_i32 s18, s90, 32
	s_lshr_b32 s18, s18, 2
	s_add_i32 s18, s18, 1
	s_cmp_gt_i32 s90, 31
	v_lshl_or_b32 v66, s91, 8, v166
	s_cselect_b32 s18, s18, 0
	s_mul_hi_u32 s19, s18, 0x6000
	s_mulk_i32 s18, 0x6000
	v_ashrrev_i32_e32 v67, 31, v66
	v_lshl_add_u32 v162, s90, 8, v164
	s_add_u32 s18, s59, s18
	v_lshlrev_b64 v[152:153], 2, v[66:67]
	v_ashrrev_i32_e32 v163, 31, v162
	s_addc_u32 s19, s62, s19
	v_lshl_add_u64 v[154:155], s[26:27], 0, v[152:153]
	v_lshlrev_b64 v[156:157], 12, v[162:163]
	v_lshl_add_u64 v[66:67], s[18:19], 0, v[152:153]
	v_lshl_add_u64 v[172:173], v[154:155], 0, v[156:157]
	global_load_dwordx4 v[78:81], v[66:67], off
	global_load_dwordx4 v[74:77], v[66:67], off offset:64
	global_load_dwordx4 v[70:73], v[66:67], off offset:512
	s_nop 0
	global_load_dwordx4 v[66:69], v[66:67], off offset:576
	s_nop 0
	global_load_dwordx4 v[158:161], v[172:173], off
	global_load_dwordx4 v[168:171], v[172:173], off offset:64
	global_load_dwordx4 v[178:181], v[172:173], off offset:512
	global_load_dwordx4 v[182:185], v[172:173], off offset:576
	v_or_b32_e32 v172, 16, v162
	v_ashrrev_i32_e32 v173, 31, v172
	v_lshlrev_b64 v[172:173], 12, v[172:173]
	v_lshl_add_u64 v[190:191], v[154:155], 0, v[172:173]
	global_load_dwordx4 v[186:189], v[190:191], off
	global_load_dwordx4 v[210:213], v[190:191], off offset:64
	global_load_dwordx4 v[214:217], v[190:191], off offset:512
	global_load_dwordx4 v[218:221], v[190:191], off offset:576
	v_or_b32_e32 v190, 32, v162
	v_ashrrev_i32_e32 v191, 31, v190
	v_lshlrev_b64 v[190:191], 12, v[190:191]
	v_or_b32_e32 v162, 48, v162
	v_lshl_add_u64 v[202:203], v[154:155], 0, v[190:191]
	v_ashrrev_i32_e32 v163, 31, v162
	global_load_dwordx4 v[222:225], v[202:203], off
	global_load_dwordx4 v[226:229], v[202:203], off offset:64
	global_load_dwordx4 v[230:233], v[202:203], off offset:512
	global_load_dwordx4 v[234:237], v[202:203], off offset:576
	v_lshlrev_b64 v[162:163], 12, v[162:163]
	v_lshl_add_u64 v[202:203], v[154:155], 0, v[162:163]
	global_load_dwordx4 v[238:241], v[202:203], off
	global_load_dwordx4 v[242:245], v[202:203], off offset:64
	global_load_dwordx4 v[246:249], v[202:203], off offset:512
	s_nop 0
	global_load_dwordx4 v[202:205], v[202:203], off offset:576
	s_mov_b64 s[18:19], 0x80000
	s_and_b64 vcc, exec, s[2:3]
	s_mov_b32 s91, s66
	s_mov_b32 s90, s67
	s_mov_b64 s[52:53], s[0:1]
	s_waitcnt vmcnt(0)
	v_pk_fma_f32 v[142:143], v[142:143], v[78:79], v[158:159]
	v_lshl_add_u64 v[158:159], s[26:27], 0, v[156:157]
	v_lshl_add_u64 v[158:159], v[158:159], 0, v[152:153]
	v_pk_fma_f32 v[128:129], v[128:129], v[72:73], v[180:181]
	v_pk_fma_f32 v[126:127], v[126:127], v[70:71], v[178:179]
	global_store_dwordx4 v[158:159], v[126:129], off offset:512
	v_pk_fma_f32 v[120:121], v[120:121], v[68:69], v[184:185]
	v_pk_fma_f32 v[112:113], v[112:113], v[72:73], v[216:217]
	v_lshl_add_u64 v[126:127], s[26:27], 0, v[172:173]
	v_lshl_add_u64 v[126:127], v[126:127], 0, v[152:153]
	v_pk_fma_f32 v[110:111], v[110:111], v[70:71], v[214:215]
	global_store_dwordx4 v[126:127], v[110:113], off offset:512
	v_pk_fma_f32 v[118:119], v[118:119], v[66:67], v[182:183]
	v_pk_fma_f32 v[104:105], v[104:105], v[68:69], v[220:221]
	v_lshl_add_u64 v[110:111], s[26:27], 0, v[190:191]
	v_lshl_add_u64 v[110:111], v[110:111], 0, v[152:153]
	v_pk_fma_f32 v[96:97], v[96:97], v[72:73], v[232:233]
	v_pk_fma_f32 v[94:95], v[94:95], v[70:71], v[230:231]
	v_pk_fma_f32 v[102:103], v[102:103], v[66:67], v[218:219]
	global_store_dwordx4 v[110:111], v[94:97], off offset:512
	v_pk_fma_f32 v[92:93], v[92:93], v[68:69], v[236:237]
	v_pk_fma_f32 v[90:91], v[90:91], v[66:67], v[234:235]
	v_lshl_add_u64 v[94:95], s[26:27], 0, v[162:163]
	global_store_dwordx4 v[158:159], v[118:121], off offset:576
	global_store_dwordx4 v[126:127], v[102:105], off offset:576
	global_store_dwordx4 v[110:111], v[90:93], off offset:576
	v_pk_fma_f32 v[120:121], v[136:137], v[80:81], v[188:189]
	v_pk_fma_f32 v[118:119], v[134:135], v[78:79], v[186:187]
	v_pk_fma_f32 v[104:105], v[124:125], v[80:81], v[224:225]
	v_pk_fma_f32 v[102:103], v[122:123], v[78:79], v[222:223]
	v_pk_fma_f32 v[92:93], v[108:109], v[80:81], v[240:241]
	v_pk_fma_f32 v[90:91], v[106:107], v[78:79], v[238:239]
	v_lshl_add_u64 v[94:95], v[94:95], 0, v[152:153]
	v_pk_fma_f32 v[144:145], v[144:145], v[80:81], v[160:161]
	v_pk_fma_f32 v[140:141], v[140:141], v[76:77], v[170:171]
	v_pk_fma_f32 v[138:139], v[138:139], v[74:75], v[168:169]
	global_store_dwordx4 v[126:127], v[118:121], off
	global_store_dwordx4 v[110:111], v[102:105], off
	global_store_dwordx4 v[94:95], v[90:93], off
	v_pk_fma_f32 v[120:121], v[132:133], v[76:77], v[212:213]
	v_pk_fma_f32 v[118:119], v[130:131], v[74:75], v[210:211]
	v_pk_fma_f32 v[104:105], v[116:117], v[76:77], v[228:229]
	v_pk_fma_f32 v[102:103], v[114:115], v[74:75], v[226:227]
	v_pk_fma_f32 v[92:93], v[100:101], v[76:77], v[244:245]
	v_pk_fma_f32 v[90:91], v[98:99], v[74:75], v[242:243]
	v_pk_fma_f32 v[88:89], v[88:89], v[72:73], v[248:249]
	v_pk_fma_f32 v[86:87], v[86:87], v[70:71], v[246:247]
	v_pk_fma_f32 v[84:85], v[84:85], v[68:69], v[204:205]
	v_pk_fma_f32 v[82:83], v[82:83], v[66:67], v[202:203]
	v_lshl_add_u64 v[162:163], v[156:157], 0, s[18:19]
	global_store_dwordx4 v[158:159], v[142:145], off
	global_store_dwordx4 v[158:159], v[138:141], off offset:64
	global_store_dwordx4 v[126:127], v[118:121], off offset:64
	global_store_dwordx4 v[110:111], v[102:105], off offset:64
	global_store_dwordx4 v[94:95], v[90:93], off offset:64
	global_store_dwordx4 v[94:95], v[86:89], off offset:512
	global_store_dwordx4 v[94:95], v[82:85], off offset:576
	s_mov_b64 s[18:19], 0x90000
	v_lshl_add_u64 v[160:161], v[156:157], 0, s[18:19]
	v_lshl_add_u64 v[82:83], v[154:155], 0, v[162:163]
	global_load_dwordx4 v[126:129], v[82:83], off
	global_load_dwordx4 v[122:125], v[82:83], off offset:64
	global_load_dwordx4 v[118:121], v[82:83], off offset:512
	global_load_dwordx4 v[106:109], v[82:83], off offset:576
	v_lshl_add_u64 v[82:83], v[154:155], 0, v[160:161]
	s_mov_b64 s[18:19], 0xa0000
	global_load_dwordx4 v[114:117], v[82:83], off
	global_load_dwordx4 v[102:105], v[82:83], off offset:64
	global_load_dwordx4 v[94:97], v[82:83], off offset:512
	global_load_dwordx4 v[86:89], v[82:83], off offset:576
	v_lshl_add_u64 v[158:159], v[156:157], 0, s[18:19]
	v_lshl_add_u64 v[82:83], v[154:155], 0, v[158:159]
	s_mov_b64 s[18:19], 0xb0000
	global_load_dwordx4 v[110:113], v[82:83], off
	global_load_dwordx4 v[98:101], v[82:83], off offset:64
	global_load_dwordx4 v[90:93], v[82:83], off offset:512
	s_nop 0
	global_load_dwordx4 v[82:85], v[82:83], off offset:576
	v_lshl_add_u64 v[156:157], v[156:157], 0, s[18:19]
	v_lshl_add_u64 v[134:135], v[154:155], 0, v[156:157]
	global_load_dwordx4 v[130:133], v[134:135], off
	global_load_dwordx4 v[142:145], v[134:135], off offset:64
	global_load_dwordx4 v[138:141], v[134:135], off offset:512
	s_nop 0
	global_load_dwordx4 v[134:137], v[134:135], off offset:576
	s_mov_b64 s[18:19], s[4:5]
	s_waitcnt vmcnt(0)
	v_pk_fma_f32 v[62:63], v[62:63], v[78:79], v[126:127]
	v_lshl_add_u64 v[126:127], s[26:27], 0, v[162:163]
	v_lshl_add_u64 v[126:127], v[126:127], 0, v[152:153]
	v_pk_fma_f32 v[52:53], v[52:53], v[72:73], v[120:121]
	v_pk_fma_f32 v[50:51], v[50:51], v[70:71], v[118:119]
	global_store_dwordx4 v[126:127], v[50:53], off offset:512
	v_pk_fma_f32 v[36:37], v[36:37], v[72:73], v[96:97]
	v_pk_fma_f32 v[34:35], v[34:35], v[70:71], v[94:95]
	v_lshl_add_u64 v[50:51], s[26:27], 0, v[160:161]
	v_lshl_add_u64 v[50:51], v[50:51], 0, v[152:153]
	global_store_dwordx4 v[50:51], v[34:37], off offset:512
	v_pk_fma_f32 v[20:21], v[20:21], v[72:73], v[92:93]
	v_pk_fma_f32 v[18:19], v[18:19], v[70:71], v[90:91]
	v_lshl_add_u64 v[34:35], s[26:27], 0, v[158:159]
	v_lshl_add_u64 v[34:35], v[34:35], 0, v[152:153]
	v_pk_fma_f32 v[44:45], v[44:45], v[68:69], v[108:109]
	v_pk_fma_f32 v[42:43], v[42:43], v[66:67], v[106:107]
	v_pk_fma_f32 v[28:29], v[28:29], v[68:69], v[88:89]
	v_pk_fma_f32 v[26:27], v[26:27], v[66:67], v[86:87]
	global_store_dwordx4 v[34:35], v[18:21], off offset:512
	v_pk_fma_f32 v[12:13], v[12:13], v[68:69], v[84:85]
	v_pk_fma_f32 v[10:11], v[10:11], v[66:67], v[82:83]
	v_lshl_add_u64 v[18:19], s[26:27], 0, v[156:157]
	global_store_dwordx4 v[126:127], v[42:45], off offset:576
	global_store_dwordx4 v[50:51], v[26:29], off offset:576
	global_store_dwordx4 v[34:35], v[10:13], off offset:576
	v_pk_fma_f32 v[44:45], v[56:57], v[80:81], v[116:117]
	v_pk_fma_f32 v[42:43], v[54:55], v[78:79], v[114:115]
	v_pk_fma_f32 v[28:29], v[40:41], v[80:81], v[112:113]
	v_pk_fma_f32 v[26:27], v[38:39], v[78:79], v[110:111]
	v_pk_fma_f32 v[12:13], v[24:25], v[80:81], v[132:133]
	v_pk_fma_f32 v[10:11], v[22:23], v[78:79], v[130:131]
	v_lshl_add_u64 v[18:19], v[18:19], 0, v[152:153]
	v_pk_fma_f32 v[64:65], v[64:65], v[80:81], v[128:129]
	v_pk_fma_f32 v[60:61], v[60:61], v[76:77], v[124:125]
	v_pk_fma_f32 v[58:59], v[58:59], v[74:75], v[122:123]
	global_store_dwordx4 v[50:51], v[42:45], off
	global_store_dwordx4 v[34:35], v[26:29], off
	global_store_dwordx4 v[18:19], v[10:13], off
	v_pk_fma_f32 v[44:45], v[48:49], v[76:77], v[104:105]
	v_pk_fma_f32 v[42:43], v[46:47], v[74:75], v[102:103]
	v_pk_fma_f32 v[28:29], v[32:33], v[76:77], v[100:101]
	v_pk_fma_f32 v[26:27], v[30:31], v[74:75], v[98:99]
	v_pk_fma_f32 v[12:13], v[16:17], v[76:77], v[144:145]
	v_pk_fma_f32 v[10:11], v[14:15], v[74:75], v[142:143]
	v_pk_fma_f32 v[8:9], v[8:9], v[72:73], v[140:141]
	v_pk_fma_f32 v[6:7], v[6:7], v[70:71], v[138:139]
	v_pk_fma_f32 v[4:5], v[4:5], v[68:69], v[136:137]
	v_pk_fma_f32 v[2:3], v[2:3], v[66:67], v[134:135]
	global_store_dwordx4 v[126:127], v[62:65], off
	global_store_dwordx4 v[126:127], v[58:61], off offset:64
	global_store_dwordx4 v[50:51], v[42:45], off offset:64
	global_store_dwordx4 v[34:35], v[26:29], off offset:64
	global_store_dwordx4 v[18:19], v[10:13], off offset:64
	global_store_dwordx4 v[18:19], v[6:9], off offset:512
	global_store_dwordx4 v[18:19], v[2:5], off offset:576
	s_cbranch_vccz .LBB0_1042
	s_waitcnt vmcnt(0)
	v_readlane_b32 s66, v252, 44
	v_readlane_b32 s64, v254, 62
	v_readlane_b32 s90, v255, 0
	s_cmpk_gt_u32 s14, 0xff
	v_readlane_b32 s67, v252, 45
	v_readlane_b32 s65, v254, 63
	v_readlane_b32 s91, v255, 1
	s_cbranch_scc1 .LBB0_1053
	s_barrier
